# epilogue waits: SwiGLU vmcnt(0)->(1), QKV vmcnt(0)->(2), FFN-down/out-proj residual loads all issued before the first wait; attention: lazy cross-half max swap
# speedup vs baseline: 1.0037x; 1.0019x over previous
; __device__ __forceinline__ unsigned cvt_pk_bf16(float lo, float hi) { const f32x2c_ v = {lo, hi}; const bf16x2c_ b = __builtin_convertvector(v, bf16x2c_); return __builtin_bit_cast(unsigned, b); }
; __device__ __forceinline__ void stat_issue(const float* ss, const Unit& u, int wr, int fr, int fq, f32x4 (&raw)[8]) {
; #pragma unroll
;     for (int ai = 0; ai < 2; ++ai)
; #pragma unroll
;         for (int m = 0; m < 4; ++m) raw[ai * 4 + m] = ((const f32x4*)(ss + (size_t)(u.pm * BM + ai * HALF + wr * 64 + m * 16 + fr) * 16))[fq];
; }
;     __device__ __forceinline__ void operator()(const f32x4 (&acc)[2][2][4][2], const Unit& u, int wr, int wc, int fr, int fq, const float (&rsv)[8]) const {
;     ...
;                 const int row = u.pm * BM + ai * HALF + wr * 64 + m * 16 + fr;
;                 const float rs = rsv[ai * 4 + m];
;                 u32x4 w;
; #pragma unroll
;                 for (int n = 0; n < 2; ++n) {
;                     const f32x4 g = acc[ai][0][m][n] * rs, up = acc[ai][1][m][n] * rs;
;                     const f32x2 g0 = {g[0], g[1]}, g1 = {g[2], g[3]}, u0 = {up[0], up[1]}, u1 = {up[2], up[3]};
;                     const f32x2 h0 = (g0 * u0) * sigmoid_pk(g0), h1 = (g1 * u1) * sigmoid_pk(g1);
;                     w[2 * n] = cvt_pk_bf16(h0.x, h0.y); w[2 * n + 1] = cvt_pk_bf16(h1.x, h1.y);
;                 }
.LBB0_203:
	v_mov_b32_e32 v202, v175
	v_mov_b32_e32 v86, v173
	s_lshl_b32 s4, s42, 8
	v_add_u32_e32 v204, s29, v86
	v_add_u32_e32 v88, s4, v204
	v_ashrrev_i32_e32 v203, 31, v202
	v_ashrrev_i32_e32 v89, 31, v88
	v_lshl_add_u64 v[86:87], v[202:203], 4, s[74:75]
	v_lshlrev_b64 v[88:89], 6, v[88:89]
	v_lshl_add_u64 v[88:89], v[86:87], 0, v[88:89]
	v_add_u32_e32 v205, 16, v204
	global_load_dwordx4 v[126:129], v[88:89], off
	v_add_u32_e32 v88, s4, v205
	v_ashrrev_i32_e32 v89, 31, v88
	v_lshlrev_b64 v[88:89], 6, v[88:89]
	v_lshl_add_u64 v[88:89], v[86:87], 0, v[88:89]
	v_add_u32_e32 v189, 32, v204
	global_load_dwordx4 v[118:121], v[88:89], off
	v_add_u32_e32 v88, s4, v189
	v_ashrrev_i32_e32 v89, 31, v88
	v_lshlrev_b64 v[88:89], 6, v[88:89]
	v_lshl_add_u64 v[88:89], v[86:87], 0, v[88:89]
	v_add_u32_e32 v188, 48, v204
	global_load_dwordx4 v[110:113], v[88:89], off
	v_add_u32_e32 v88, s4, v188
	v_ashrrev_i32_e32 v89, 31, v88
	v_lshlrev_b64 v[88:89], 6, v[88:89]
	v_lshl_add_u64 v[88:89], v[86:87], 0, v[88:89]
	v_add_u32_e32 v187, 0x80, v204
	global_load_dwordx4 v[106:109], v[88:89], off
	v_add_u32_e32 v88, s4, v187
	v_ashrrev_i32_e32 v89, 31, v88
	v_lshlrev_b64 v[88:89], 6, v[88:89]
	v_lshl_add_u64 v[88:89], v[86:87], 0, v[88:89]
	v_add_u32_e32 v185, 0x90, v204
	global_load_dwordx4 v[102:105], v[88:89], off
	v_add_u32_e32 v88, s4, v185
	v_ashrrev_i32_e32 v89, 31, v88
	v_lshlrev_b64 v[88:89], 6, v[88:89]
	v_lshl_add_u64 v[88:89], v[86:87], 0, v[88:89]
	v_add_u32_e32 v183, 0xa0, v204
	global_load_dwordx4 v[98:101], v[88:89], off
	v_add_u32_e32 v88, s4, v183
	v_ashrrev_i32_e32 v89, 31, v88
	v_lshlrev_b64 v[88:89], 6, v[88:89]
	v_lshl_add_u64 v[88:89], v[86:87], 0, v[88:89]
	v_add_u32_e32 v181, 0xb0, v204
	global_load_dwordx4 v[94:97], v[88:89], off
	v_add_u32_e32 v88, s4, v181
	v_ashrrev_i32_e32 v89, 31, v88
	v_lshlrev_b64 v[88:89], 6, v[88:89]
	v_lshl_add_u64 v[86:87], v[86:87], 0, v[88:89]
	global_load_dwordx4 v[86:89], v[86:87], off
	v_pk_mul_f32 v[158:159], v[186:187], v[158:159] op_sel_hi:[0,1]
	v_pk_mul_f32 v[154:155], v[186:187], v[154:155] op_sel_hi:[0,1]
	v_pk_mul_f32 v[150:151], v[186:187], v[150:151] op_sel_hi:[0,1]
	v_pk_mul_f32 v[146:147], v[186:187], v[146:147] op_sel_hi:[0,1]
	v_pk_mul_f32 v[154:155], v[154:155], v[158:159]
	v_pk_mul_f32 v[158:159], v[158:159], s[90:91] op_sel_hi:[1,0]
	v_pk_mul_f32 v[146:147], v[146:147], v[150:151]
	v_pk_mul_f32 v[150:151], v[150:151], s[90:91] op_sel_hi:[1,0]
	v_exp_f32_e32 v158, v158
	v_exp_f32_e32 v159, v159
	v_exp_f32_e32 v150, v150
	v_exp_f32_e32 v151, v151
	v_pk_mul_f32 v[12:13], v[172:173], v[12:13] op_sel_hi:[0,1]
	v_pk_mul_f32 v[8:9], v[172:173], v[8:9] op_sel_hi:[0,1]
	v_pk_mul_f32 v[8:9], v[8:9], v[12:13]
	v_pk_mul_f32 v[12:13], v[12:13], s[90:91] op_sel_hi:[1,0]
	v_pk_add_f32 v[158:159], v[158:159], 1.0 op_sel_hi:[1,0]
	v_exp_f32_e32 v12, v12
	v_exp_f32_e32 v13, v13
	v_pk_add_f32 v[150:151], v[150:151], 1.0 op_sel_hi:[1,0]
	v_rcp_f32_e32 v158, v158
	v_rcp_f32_e32 v159, v159
	v_rcp_f32_e32 v150, v150
	v_rcp_f32_e32 v151, v151
	v_pk_mul_f32 v[4:5], v[172:173], v[4:5] op_sel_hi:[0,1]
	v_pk_mul_f32 v[0:1], v[172:173], v[0:1] op_sel_hi:[0,1]
	v_pk_mul_f32 v[0:1], v[0:1], v[4:5]
	v_pk_mul_f32 v[4:5], v[4:5], s[90:91] op_sel_hi:[1,0]
	v_pk_add_f32 v[12:13], v[12:13], 1.0 op_sel_hi:[1,0]
	v_exp_f32_e32 v4, v4
	v_exp_f32_e32 v5, v5
	v_pk_mul_f32 v[160:161], v[186:187], v[160:161] op_sel_hi:[0,1]
	v_pk_mul_f32 v[152:153], v[186:187], v[152:153] op_sel_hi:[0,1]
	v_rcp_f32_e32 v12, v12
	v_rcp_f32_e32 v13, v13
	v_pk_mul_f32 v[154:155], v[154:155], v[158:159]
	v_pk_mul_f32 v[158:159], v[160:161], s[90:91] op_sel_hi:[1,0]
	v_pk_mul_f32 v[146:147], v[146:147], v[150:151]
	v_pk_mul_f32 v[150:151], v[152:153], s[90:91] op_sel_hi:[1,0]
	v_exp_f32_e32 v158, v158
	v_exp_f32_e32 v159, v159
	v_exp_f32_e32 v150, v150
	v_exp_f32_e32 v151, v151
	v_pk_mul_f32 v[14:15], v[172:173], v[14:15] op_sel_hi:[0,1]
	v_pk_add_f32 v[4:5], v[4:5], 1.0 op_sel_hi:[1,0]
	v_pk_mul_f32 v[142:143], v[184:185], v[142:143] op_sel_hi:[0,1]
	v_pk_mul_f32 v[138:139], v[184:185], v[138:139] op_sel_hi:[0,1]
	v_pk_mul_f32 v[122:123], v[182:183], v[122:123] op_sel_hi:[0,1]
	v_pk_mul_f32 v[114:115], v[182:183], v[114:115] op_sel_hi:[0,1]
	v_pk_mul_f32 v[78:79], v[180:181], v[78:79] op_sel_hi:[0,1]
	v_pk_mul_f32 v[74:75], v[180:181], v[74:75] op_sel_hi:[0,1]
	v_pk_mul_f32 v[60:61], v[178:179], v[60:61] op_sel_hi:[0,1]
	v_pk_mul_f32 v[56:57], v[178:179], v[56:57] op_sel_hi:[0,1]
	v_pk_mul_f32 v[44:45], v[176:177], v[44:45] op_sel_hi:[0,1]
	v_pk_mul_f32 v[40:41], v[176:177], v[40:41] op_sel_hi:[0,1]
	v_pk_mul_f32 v[28:29], v[174:175], v[28:29] op_sel_hi:[0,1]
	v_pk_mul_f32 v[24:25], v[174:175], v[24:25] op_sel_hi:[0,1]
	v_pk_mul_f32 v[8:9], v[8:9], v[12:13]
	v_pk_mul_f32 v[12:13], v[14:15], s[90:91] op_sel_hi:[1,0]
	v_rcp_f32_e32 v4, v4
	v_rcp_f32_e32 v5, v5
	v_pk_mul_f32 v[138:139], v[138:139], v[142:143]
	v_pk_mul_f32 v[142:143], v[142:143], s[90:91] op_sel_hi:[1,0]
	v_pk_mul_f32 v[114:115], v[114:115], v[122:123]
	v_pk_mul_f32 v[122:123], v[122:123], s[90:91] op_sel_hi:[1,0]
	v_pk_mul_f32 v[74:75], v[74:75], v[78:79]
	v_pk_mul_f32 v[78:79], v[78:79], s[90:91] op_sel_hi:[1,0]
	v_pk_mul_f32 v[56:57], v[56:57], v[60:61]
	v_pk_mul_f32 v[60:61], v[60:61], s[90:91] op_sel_hi:[1,0]
	v_pk_mul_f32 v[40:41], v[40:41], v[44:45]
	v_pk_mul_f32 v[44:45], v[44:45], s[90:91] op_sel_hi:[1,0]
	v_pk_mul_f32 v[24:25], v[24:25], v[28:29]
	v_pk_mul_f32 v[28:29], v[28:29], s[90:91] op_sel_hi:[1,0]
	v_exp_f32_e32 v12, v12
	v_exp_f32_e32 v13, v13
	v_pk_add_f32 v[158:159], v[158:159], 1.0 op_sel_hi:[1,0]
	v_pk_add_f32 v[150:151], v[150:151], 1.0 op_sel_hi:[1,0]
; __device__ __forceinline__ unsigned cvt_pk_bf16(float lo, float hi) { const f32x2c_ v = {lo, hi}; const bf16x2c_ b = __builtin_convertvector(v, bf16x2c_); return __builtin_bit_cast(unsigned, b); }
;     __device__ __forceinline__ void operator()(const f32x4 (&acc)[2][2][4][2], const Unit& u, int wr, int wc, int fr, int fq, const float (&rsv)[8]) const {
;     ...
;                 const int row = u.pm * BM + ai * HALF + wr * 64 + m * 16 + fr;
;                 const float rs = rsv[ai * 4 + m];
;                 u32x4 w;
; #pragma unroll
;                 for (int n = 0; n < 2; ++n) {
;                     const f32x4 g = acc[ai][0][m][n] * rs, up = acc[ai][1][m][n] * rs;
;                     const f32x2 g0 = {g[0], g[1]}, g1 = {g[2], g[3]}, u0 = {up[0], up[1]}, u1 = {up[2], up[3]};
;                     const f32x2 h0 = (g0 * u0) * sigmoid_pk(g0), h1 = (g1 * u1) * sigmoid_pk(g1);
;                     w[2 * n] = cvt_pk_bf16(h0.x, h0.y); w[2 * n + 1] = cvt_pk_bf16(h1.x, h1.y);
;                 }
;                 *(u32x4*)(hid + (size_t)row * ldh + u.pn * 128 + wc * 32 + 8 * fq) = w;
	v_exp_f32_e32 v142, v142
	v_exp_f32_e32 v143, v143
	v_exp_f32_e32 v122, v122
	v_exp_f32_e32 v123, v123
	v_exp_f32_e32 v78, v78
	v_exp_f32_e32 v79, v79
	v_exp_f32_e32 v60, v60
	v_exp_f32_e32 v61, v61
	v_exp_f32_e32 v44, v44
	v_exp_f32_e32 v45, v45
	v_exp_f32_e32 v28, v28
	v_exp_f32_e32 v29, v29
	v_rcp_f32_e32 v158, v158
	v_rcp_f32_e32 v159, v159
	v_rcp_f32_e32 v150, v150
	v_rcp_f32_e32 v151, v151
	v_pk_mul_f32 v[6:7], v[172:173], v[6:7] op_sel_hi:[0,1]
	v_pk_mul_f32 v[134:135], v[184:185], v[134:135] op_sel_hi:[0,1]
	v_pk_mul_f32 v[130:131], v[184:185], v[130:131] op_sel_hi:[0,1]
	v_pk_mul_f32 v[90:91], v[182:183], v[90:91] op_sel_hi:[0,1]
	v_pk_mul_f32 v[82:83], v[182:183], v[82:83] op_sel_hi:[0,1]
	v_pk_mul_f32 v[70:71], v[180:181], v[70:71] op_sel_hi:[0,1]
	v_pk_mul_f32 v[66:67], v[180:181], v[66:67] op_sel_hi:[0,1]
	v_pk_mul_f32 v[52:53], v[178:179], v[52:53] op_sel_hi:[0,1]
	v_pk_mul_f32 v[48:49], v[178:179], v[48:49] op_sel_hi:[0,1]
	v_pk_mul_f32 v[36:37], v[176:177], v[36:37] op_sel_hi:[0,1]
	v_pk_mul_f32 v[32:33], v[176:177], v[32:33] op_sel_hi:[0,1]
	v_pk_mul_f32 v[20:21], v[174:175], v[20:21] op_sel_hi:[0,1]
	v_pk_mul_f32 v[16:17], v[174:175], v[16:17] op_sel_hi:[0,1]
	v_pk_mul_f32 v[0:1], v[0:1], v[4:5]
	v_pk_mul_f32 v[4:5], v[6:7], s[90:91] op_sel_hi:[1,0]
	v_pk_mul_f32 v[156:157], v[186:187], v[156:157] op_sel_hi:[0,1]
	v_pk_mul_f32 v[148:149], v[186:187], v[148:149] op_sel_hi:[0,1]
	v_pk_mul_f32 v[130:131], v[130:131], v[134:135]
	v_pk_mul_f32 v[134:135], v[134:135], s[90:91] op_sel_hi:[1,0]
	v_pk_mul_f32 v[82:83], v[82:83], v[90:91]
	v_pk_mul_f32 v[90:91], v[90:91], s[90:91] op_sel_hi:[1,0]
	v_pk_mul_f32 v[66:67], v[66:67], v[70:71]
	v_pk_mul_f32 v[70:71], v[70:71], s[90:91] op_sel_hi:[1,0]
	v_pk_mul_f32 v[48:49], v[48:49], v[52:53]
	v_pk_mul_f32 v[52:53], v[52:53], s[90:91] op_sel_hi:[1,0]
	v_pk_mul_f32 v[32:33], v[32:33], v[36:37]
	v_pk_mul_f32 v[36:37], v[36:37], s[90:91] op_sel_hi:[1,0]
	v_pk_mul_f32 v[16:17], v[16:17], v[20:21]
	v_pk_mul_f32 v[20:21], v[20:21], s[90:91] op_sel_hi:[1,0]
	v_pk_add_f32 v[12:13], v[12:13], 1.0 op_sel_hi:[1,0]
	v_exp_f32_e32 v4, v4
	v_exp_f32_e32 v5, v5
	v_pk_mul_f32 v[156:157], v[156:157], v[160:161]
	v_pk_mul_f32 v[148:149], v[148:149], v[152:153]
	v_pk_add_f32 v[142:143], v[142:143], 1.0 op_sel_hi:[1,0]
	v_exp_f32_e32 v134, v134
	v_exp_f32_e32 v135, v135
	v_pk_add_f32 v[122:123], v[122:123], 1.0 op_sel_hi:[1,0]
	v_exp_f32_e32 v90, v90
	v_exp_f32_e32 v91, v91
	v_pk_add_f32 v[78:79], v[78:79], 1.0 op_sel_hi:[1,0]
	v_exp_f32_e32 v70, v70
	v_exp_f32_e32 v71, v71
	v_pk_add_f32 v[60:61], v[60:61], 1.0 op_sel_hi:[1,0]
	v_exp_f32_e32 v52, v52
	v_exp_f32_e32 v53, v53
	v_pk_add_f32 v[44:45], v[44:45], 1.0 op_sel_hi:[1,0]
	v_exp_f32_e32 v36, v36
	v_exp_f32_e32 v37, v37
	v_pk_add_f32 v[28:29], v[28:29], 1.0 op_sel_hi:[1,0]
	v_exp_f32_e32 v20, v20
	v_exp_f32_e32 v21, v21
	v_rcp_f32_e32 v12, v12
	v_rcp_f32_e32 v13, v13
	v_pk_mul_f32 v[156:157], v[156:157], v[158:159]
	v_pk_mul_f32 v[148:149], v[148:149], v[150:151]
	s_lshl_b32 s17, s41, 8
	v_rcp_f32_e32 v142, v142
	v_rcp_f32_e32 v143, v143
	v_rcp_f32_e32 v122, v122
	v_rcp_f32_e32 v123, v123
	v_rcp_f32_e32 v78, v78
	v_rcp_f32_e32 v79, v79
	v_rcp_f32_e32 v60, v60
	v_rcp_f32_e32 v61, v61
	v_rcp_f32_e32 v44, v44
	v_rcp_f32_e32 v45, v45
	v_rcp_f32_e32 v28, v28
	v_rcp_f32_e32 v29, v29
	v_cvt_pk_bf16_f32 v154, v154, v155
	v_cvt_pk_bf16_f32 v155, v156, v157
	v_cvt_pk_bf16_f32 v156, v146, v147
	v_cvt_pk_bf16_f32 v157, v148, v149
	v_add_u32_e32 v148, s17, v204
	v_mov_b64_e32 v[146:147], s[0:1]
	v_pk_mul_f32 v[10:11], v[172:173], v[10:11] op_sel_hi:[0,1]
	v_mad_i64_i32 v[148:149], s[4:5], v148, s33, v[146:147]
	v_pk_mul_f32 v[10:11], v[10:11], v[14:15]
	v_pk_add_f32 v[4:5], v[4:5], 1.0 op_sel_hi:[1,0]
	s_lshl_b32 s4, s2, 7
	v_pk_mul_f32 v[144:145], v[184:185], v[144:145] op_sel_hi:[0,1]
	v_pk_add_f32 v[134:135], v[134:135], 1.0 op_sel_hi:[1,0]
	v_pk_mul_f32 v[124:125], v[182:183], v[124:125] op_sel_hi:[0,1]
	v_pk_add_f32 v[90:91], v[90:91], 1.0 op_sel_hi:[1,0]
	v_pk_mul_f32 v[80:81], v[180:181], v[80:81] op_sel_hi:[0,1]
	v_pk_add_f32 v[70:71], v[70:71], 1.0 op_sel_hi:[1,0]
	v_pk_mul_f32 v[62:63], v[178:179], v[62:63] op_sel_hi:[0,1]
	v_pk_add_f32 v[52:53], v[52:53], 1.0 op_sel_hi:[1,0]
	v_pk_mul_f32 v[46:47], v[176:177], v[46:47] op_sel_hi:[0,1]
	v_pk_add_f32 v[36:37], v[36:37], 1.0 op_sel_hi:[1,0]
	v_pk_mul_f32 v[30:31], v[174:175], v[30:31] op_sel_hi:[0,1]
	v_pk_add_f32 v[20:21], v[20:21], 1.0 op_sel_hi:[1,0]
	v_pk_mul_f32 v[10:11], v[10:11], v[12:13]
	v_rcp_f32_e32 v4, v4
	v_rcp_f32_e32 v5, v5
	s_ashr_i32 s5, s4, 31
	v_pk_mul_f32 v[138:139], v[138:139], v[142:143]
	v_pk_mul_f32 v[142:143], v[144:145], s[90:91] op_sel_hi:[1,0]
	v_rcp_f32_e32 v134, v134
	v_rcp_f32_e32 v135, v135
	v_pk_mul_f32 v[114:115], v[114:115], v[122:123]
	v_pk_mul_f32 v[122:123], v[124:125], s[90:91] op_sel_hi:[1,0]
	v_rcp_f32_e32 v90, v90
	v_rcp_f32_e32 v91, v91
	v_pk_mul_f32 v[74:75], v[74:75], v[78:79]
	v_pk_mul_f32 v[78:79], v[80:81], s[90:91] op_sel_hi:[1,0]
	v_rcp_f32_e32 v70, v70
	v_rcp_f32_e32 v71, v71
	v_pk_mul_f32 v[56:57], v[56:57], v[60:61]
	v_pk_mul_f32 v[60:61], v[62:63], s[90:91] op_sel_hi:[1,0]
	v_rcp_f32_e32 v52, v52
	v_rcp_f32_e32 v53, v53
	v_pk_mul_f32 v[40:41], v[40:41], v[44:45]
	v_pk_mul_f32 v[44:45], v[46:47], s[90:91] op_sel_hi:[1,0]
	v_rcp_f32_e32 v36, v36
	v_rcp_f32_e32 v37, v37
	v_pk_mul_f32 v[24:25], v[24:25], v[28:29]
	v_pk_mul_f32 v[28:29], v[30:31], s[90:91] op_sel_hi:[1,0]
	v_rcp_f32_e32 v20, v20
	v_rcp_f32_e32 v21, v21
	v_cvt_pk_bf16_f32 v8, v8, v9
	v_cvt_pk_bf16_f32 v9, v10, v11
	v_cvt_pk_bf16_f32 v10, v0, v1
	v_add_u32_e32 v0, s17, v181
; __device__ __forceinline__ unsigned cvt_pk_bf16(float lo, float hi) { const f32x2c_ v = {lo, hi}; const bf16x2c_ b = __builtin_convertvector(v, bf16x2c_); return __builtin_bit_cast(unsigned, b); }
; template <int N> __device__ __forceinline__ float sxor(float v) { static_assert(N > 0 && N < 32, "sxor"); return __int_as_float(__builtin_amdgcn_ds_swizzle(__float_as_int(v), 0x1f | (N << 10))); }
; __device__ __forceinline__ float sum32(float v) { const auto rr = __builtin_amdgcn_permlane32_swap(__float_as_uint(v), __float_as_uint(v), false, false); return __uint_as_float(rr[0]) + __uint_as_float(rr[1]); }
; __device__ __forceinline__ float hsum4(f32x4 a) { return (a[0] + a[1]) + (a[2] + a[3]); }
; __device__ __forceinline__ void stat_finish(const f32x4 (&raw)[8], float (&rs)[8], float invn) {
; #pragma unroll
;     for (int r = 0; r < 8; ++r) { float s = hsum4(raw[r]); s += sxor<16>(s); s = sum32(s); rs[r] = __builtin_amdgcn_rsqf(s * invn + EPS); }
; }
;     __device__ __forceinline__ void operator()(const f32x4 (&acc)[2][2][4][2], const Unit& u, int wr, int wc, int fr, int fq, const float (&rsv)[8]) const {
;     ...
;                     const f32x4 g = acc[ai][0][m][n] * rs, up = acc[ai][1][m][n] * rs;
;                     const f32x2 g0 = {g[0], g[1]}, g1 = {g[2], g[3]}, u0 = {up[0], up[1]}, u1 = {up[2], up[3]};
;                     const f32x2 h0 = (g0 * u0) * sigmoid_pk(g0), h1 = (g1 * u1) * sigmoid_pk(g1);
;                     w[2 * n] = cvt_pk_bf16(h0.x, h0.y); w[2 * n + 1] = cvt_pk_bf16(h1.x, h1.y);
;                 }
;                 *(u32x4*)(hid + (size_t)row * ldh + u.pn * 128 + wc * 32 + 8 * fq) = w;
	v_lshlrev_b32_e32 v202, 3, v202
	s_lshl_b64 s[4:5], s[4:5], 1
	v_exp_f32_e32 v142, v142
	v_exp_f32_e32 v143, v143
	v_exp_f32_e32 v122, v122
	v_exp_f32_e32 v123, v123
	v_exp_f32_e32 v78, v78
	v_exp_f32_e32 v79, v79
	v_exp_f32_e32 v60, v60
	v_exp_f32_e32 v61, v61
	v_exp_f32_e32 v44, v44
	v_exp_f32_e32 v45, v45
	v_exp_f32_e32 v28, v28
	v_exp_f32_e32 v29, v29
	v_pk_mul_f32 v[2:3], v[172:173], v[2:3] op_sel_hi:[0,1]
	v_mad_i64_i32 v[0:1], s[24:25], v0, s33, v[146:147]
	v_ashrrev_i32_e32 v203, 31, v202
	v_lshl_add_u64 v[148:149], v[148:149], 0, s[4:5]
	v_pk_mul_f32 v[2:3], v[2:3], v[6:7]
	v_lshl_add_u64 v[0:1], v[0:1], 0, s[4:5]
	v_lshl_add_u64 v[150:151], v[148:149], 0, s[78:79]
	v_lshlrev_b64 v[148:149], 1, v[202:203]
	v_pk_mul_f32 v[136:137], v[184:185], v[136:137] op_sel_hi:[0,1]
	v_pk_mul_f32 v[92:93], v[182:183], v[92:93] op_sel_hi:[0,1]
	v_pk_mul_f32 v[72:73], v[180:181], v[72:73] op_sel_hi:[0,1]
	v_pk_mul_f32 v[54:55], v[178:179], v[54:55] op_sel_hi:[0,1]
	v_pk_mul_f32 v[38:39], v[176:177], v[38:39] op_sel_hi:[0,1]
	v_pk_mul_f32 v[22:23], v[174:175], v[22:23] op_sel_hi:[0,1]
	v_pk_mul_f32 v[2:3], v[2:3], v[4:5]
	v_lshl_add_u64 v[0:1], v[0:1], 0, s[78:79]
	v_pk_mul_f32 v[130:131], v[130:131], v[134:135]
	v_pk_mul_f32 v[134:135], v[136:137], s[90:91] op_sel_hi:[1,0]
	v_pk_mul_f32 v[82:83], v[82:83], v[90:91]
	v_pk_mul_f32 v[90:91], v[92:93], s[90:91] op_sel_hi:[1,0]
	v_pk_mul_f32 v[66:67], v[66:67], v[70:71]
	v_pk_mul_f32 v[70:71], v[72:73], s[90:91] op_sel_hi:[1,0]
	v_pk_mul_f32 v[48:49], v[48:49], v[52:53]
	v_pk_mul_f32 v[52:53], v[54:55], s[90:91] op_sel_hi:[1,0]
	v_pk_mul_f32 v[32:33], v[32:33], v[36:37]
	v_pk_mul_f32 v[36:37], v[38:39], s[90:91] op_sel_hi:[1,0]
	v_pk_mul_f32 v[16:17], v[16:17], v[20:21]
	v_pk_mul_f32 v[20:21], v[22:23], s[90:91] op_sel_hi:[1,0]
	v_cvt_pk_bf16_f32 v11, v2, v3
	v_lshl_add_u64 v[0:1], v[0:1], 0, v[148:149]
	v_pk_add_f32 v[142:143], v[142:143], 1.0 op_sel_hi:[1,0]
	v_exp_f32_e32 v134, v134
	v_exp_f32_e32 v135, v135
	v_pk_add_f32 v[122:123], v[122:123], 1.0 op_sel_hi:[1,0]
	v_exp_f32_e32 v90, v90
	v_exp_f32_e32 v91, v91
	v_pk_add_f32 v[78:79], v[78:79], 1.0 op_sel_hi:[1,0]
	v_exp_f32_e32 v70, v70
	v_exp_f32_e32 v71, v71
	v_pk_add_f32 v[60:61], v[60:61], 1.0 op_sel_hi:[1,0]
	v_exp_f32_e32 v52, v52
	v_exp_f32_e32 v53, v53
	v_pk_add_f32 v[44:45], v[44:45], 1.0 op_sel_hi:[1,0]
	v_exp_f32_e32 v36, v36
	v_exp_f32_e32 v37, v37
	v_pk_add_f32 v[28:29], v[28:29], 1.0 op_sel_hi:[1,0]
	v_exp_f32_e32 v20, v20
	v_exp_f32_e32 v21, v21
	global_store_dwordx4 v[0:1], v[8:11], off
	s_waitcnt vmcnt(1)
	v_mov_b32_e32 v0, v127
	v_mov_b32_e32 v1, v128
	v_mov_b32_e32 v127, v129
	v_mov_b32_e32 v2, v119
	v_mov_b32_e32 v3, v120
	v_mov_b32_e32 v119, v121
	v_mov_b32_e32 v4, v111
	v_mov_b32_e32 v5, v112
	v_mov_b32_e32 v111, v113
	v_mov_b32_e32 v6, v107
	v_mov_b32_e32 v7, v108
	v_mov_b32_e32 v107, v109
	v_mov_b32_e32 v8, v103
	v_mov_b32_e32 v9, v104
	v_mov_b32_e32 v103, v105
	v_mov_b32_e32 v10, v99
	v_mov_b32_e32 v11, v100
	v_mov_b32_e32 v99, v101
	v_mov_b32_e32 v12, v95
	v_mov_b32_e32 v13, v96
	v_mov_b32_e32 v95, v97
	v_mov_b32_e32 v14, v87
	v_mov_b32_e32 v15, v88
	v_mov_b32_e32 v87, v89
	v_rcp_f32_e32 v142, v142
	v_rcp_f32_e32 v143, v143
	v_rcp_f32_e32 v122, v122
	v_rcp_f32_e32 v123, v123
	v_rcp_f32_e32 v78, v78
	v_rcp_f32_e32 v79, v79
	v_rcp_f32_e32 v60, v60
	v_rcp_f32_e32 v61, v61
	v_rcp_f32_e32 v44, v44
	v_rcp_f32_e32 v45, v45
	v_rcp_f32_e32 v28, v28
	v_rcp_f32_e32 v29, v29
	v_pk_add_f32 v[0:1], v[0:1], v[126:127]
	v_pk_add_f32 v[2:3], v[2:3], v[118:119]
	v_pk_add_f32 v[4:5], v[4:5], v[110:111]
	v_pk_add_f32 v[6:7], v[6:7], v[106:107]
	v_pk_add_f32 v[8:9], v[8:9], v[102:103]
	v_pk_add_f32 v[10:11], v[10:11], v[98:99]
	v_pk_add_f32 v[12:13], v[12:13], v[94:95]
	v_pk_add_f32 v[14:15], v[14:15], v[86:87]
	v_add_f32_e32 v0, v0, v1
	v_add_f32_e32 v2, v2, v3
	v_add_f32_e32 v4, v4, v5
	v_add_f32_e32 v6, v6, v7
	v_add_f32_e32 v8, v8, v9
	v_add_f32_e32 v10, v10, v11
	v_add_f32_e32 v12, v12, v13
	v_add_f32_e32 v14, v14, v15
	v_pk_mul_f32 v[140:141], v[184:185], v[140:141] op_sel_hi:[0,1]
	v_pk_mul_f32 v[116:117], v[182:183], v[116:117] op_sel_hi:[0,1]
	v_pk_mul_f32 v[76:77], v[180:181], v[76:77] op_sel_hi:[0,1]
	v_pk_mul_f32 v[58:59], v[178:179], v[58:59] op_sel_hi:[0,1]
	v_pk_mul_f32 v[42:43], v[176:177], v[42:43] op_sel_hi:[0,1]
	v_pk_mul_f32 v[26:27], v[174:175], v[26:27] op_sel_hi:[0,1]
	ds_swizzle_b32 v1, v0 offset:swizzle(SWAP,16)
	ds_swizzle_b32 v3, v2 offset:swizzle(SWAP,16)
	ds_swizzle_b32 v5, v4 offset:swizzle(SWAP,16)
	ds_swizzle_b32 v7, v6 offset:swizzle(SWAP,16)
	ds_swizzle_b32 v9, v8 offset:swizzle(SWAP,16)
	ds_swizzle_b32 v11, v10 offset:swizzle(SWAP,16)
	ds_swizzle_b32 v13, v12 offset:swizzle(SWAP,16)
	ds_swizzle_b32 v15, v14 offset:swizzle(SWAP,16)
	v_pk_mul_f32 v[140:141], v[140:141], v[144:145]
	v_pk_add_f32 v[134:135], v[134:135], 1.0 op_sel_hi:[1,0]
	v_pk_mul_f32 v[116:117], v[116:117], v[124:125]
	v_pk_add_f32 v[90:91], v[90:91], 1.0 op_sel_hi:[1,0]
	v_pk_mul_f32 v[76:77], v[76:77], v[80:81]
	v_pk_add_f32 v[70:71], v[70:71], 1.0 op_sel_hi:[1,0]
	v_pk_mul_f32 v[58:59], v[58:59], v[62:63]
	v_pk_add_f32 v[52:53], v[52:53], 1.0 op_sel_hi:[1,0]
; __device__ __forceinline__ unsigned cvt_pk_bf16(float lo, float hi) { const f32x2c_ v = {lo, hi}; const bf16x2c_ b = __builtin_convertvector(v, bf16x2c_); return __builtin_bit_cast(unsigned, b); }
; template <int N> __device__ __forceinline__ float sxor(float v) { static_assert(N > 0 && N < 32, "sxor"); return __int_as_float(__builtin_amdgcn_ds_swizzle(__float_as_int(v), 0x1f | (N << 10))); }
; __device__ __forceinline__ float sum32(float v) { const auto rr = __builtin_amdgcn_permlane32_swap(__float_as_uint(v), __float_as_uint(v), false, false); return __uint_as_float(rr[0]) + __uint_as_float(rr[1]); }
; __device__ __forceinline__ float hsum4(f32x4 a) { return (a[0] + a[1]) + (a[2] + a[3]); }
; __device__ __forceinline__ void stat_finish(const f32x4 (&raw)[8], float (&rs)[8], float invn) {
; #pragma unroll
;     for (int r = 0; r < 8; ++r) { float s = hsum4(raw[r]); s += sxor<16>(s); s = sum32(s); rs[r] = __builtin_amdgcn_rsqf(s * invn + EPS); }
; }
;     __device__ __forceinline__ void operator()(const f32x4 (&acc)[2][2][4][2], const Unit& u, int wr, int wc, int fr, int fq, const float (&rsv)[8]) const {
;     ...
;                     const f32x4 g = acc[ai][0][m][n] * rs, up = acc[ai][1][m][n] * rs;
;                     const f32x2 g0 = {g[0], g[1]}, g1 = {g[2], g[3]}, u0 = {up[0], up[1]}, u1 = {up[2], up[3]};
;                     const f32x2 h0 = (g0 * u0) * sigmoid_pk(g0), h1 = (g1 * u1) * sigmoid_pk(g1);
;                     w[2 * n] = cvt_pk_bf16(h0.x, h0.y); w[2 * n + 1] = cvt_pk_bf16(h1.x, h1.y);
;                 }
;                 *(u32x4*)(hid + (size_t)row * ldh + u.pn * 128 + wc * 32 + 8 * fq) = w;
	v_pk_mul_f32 v[42:43], v[42:43], v[46:47]
	v_pk_add_f32 v[36:37], v[36:37], 1.0 op_sel_hi:[1,0]
	v_pk_mul_f32 v[26:27], v[26:27], v[30:31]
	v_pk_add_f32 v[20:21], v[20:21], 1.0 op_sel_hi:[1,0]
	v_pk_mul_f32 v[140:141], v[140:141], v[142:143]
	v_rcp_f32_e32 v134, v134
	v_rcp_f32_e32 v135, v135
	v_pk_mul_f32 v[116:117], v[116:117], v[122:123]
	v_rcp_f32_e32 v90, v90
	v_rcp_f32_e32 v91, v91
	v_pk_mul_f32 v[76:77], v[76:77], v[78:79]
	v_rcp_f32_e32 v70, v70
	v_rcp_f32_e32 v71, v71
	v_pk_mul_f32 v[58:59], v[58:59], v[60:61]
	v_rcp_f32_e32 v52, v52
	v_rcp_f32_e32 v53, v53
	v_pk_mul_f32 v[42:43], v[42:43], v[44:45]
	v_rcp_f32_e32 v36, v36
	v_rcp_f32_e32 v37, v37
	v_pk_mul_f32 v[26:27], v[26:27], v[28:29]
	v_rcp_f32_e32 v20, v20
	v_rcp_f32_e32 v21, v21
	v_cvt_pk_bf16_f32 v138, v138, v139
	v_cvt_pk_bf16_f32 v139, v140, v141
	v_cvt_pk_bf16_f32 v140, v130, v131
	v_add_u32_e32 v130, s17, v205
	v_cvt_pk_bf16_f32 v114, v114, v115
	v_cvt_pk_bf16_f32 v115, v116, v117
	v_cvt_pk_bf16_f32 v116, v82, v83
	v_add_u32_e32 v82, s17, v189
	v_cvt_pk_bf16_f32 v74, v74, v75
	v_cvt_pk_bf16_f32 v75, v76, v77
	v_cvt_pk_bf16_f32 v76, v66, v67
	v_add_u32_e32 v66, s17, v188
	v_cvt_pk_bf16_f32 v56, v56, v57
	v_cvt_pk_bf16_f32 v57, v58, v59
	v_cvt_pk_bf16_f32 v58, v48, v49
	v_add_u32_e32 v48, s17, v187
	v_cvt_pk_bf16_f32 v40, v40, v41
	v_cvt_pk_bf16_f32 v41, v42, v43
	v_cvt_pk_bf16_f32 v42, v32, v33
	v_add_u32_e32 v32, s17, v185
	v_cvt_pk_bf16_f32 v24, v24, v25
	v_cvt_pk_bf16_f32 v25, v26, v27
	v_cvt_pk_bf16_f32 v26, v16, v17
	v_add_u32_e32 v16, s17, v183
	v_pk_mul_f32 v[132:133], v[184:185], v[132:133] op_sel_hi:[0,1]
	v_mad_i64_i32 v[130:131], s[24:25], v130, s33, v[146:147]
	v_pk_mul_f32 v[84:85], v[182:183], v[84:85] op_sel_hi:[0,1]
	v_mad_i64_i32 v[82:83], s[24:25], v82, s33, v[146:147]
	v_pk_mul_f32 v[68:69], v[180:181], v[68:69] op_sel_hi:[0,1]
	v_mad_i64_i32 v[66:67], s[24:25], v66, s33, v[146:147]
	v_pk_mul_f32 v[50:51], v[178:179], v[50:51] op_sel_hi:[0,1]
	v_mad_i64_i32 v[48:49], s[24:25], v48, s33, v[146:147]
	v_pk_mul_f32 v[34:35], v[176:177], v[34:35] op_sel_hi:[0,1]
	v_mad_i64_i32 v[32:33], s[24:25], v32, s33, v[146:147]
	v_pk_mul_f32 v[18:19], v[174:175], v[18:19] op_sel_hi:[0,1]
	v_mad_i64_i32 v[16:17], s[24:25], v16, s33, v[146:147]
	v_pk_mul_f32 v[132:133], v[132:133], v[136:137]
	v_lshl_add_u64 v[130:131], v[130:131], 0, s[4:5]
	v_pk_mul_f32 v[84:85], v[84:85], v[92:93]
	v_lshl_add_u64 v[82:83], v[82:83], 0, s[4:5]
	v_pk_mul_f32 v[68:69], v[68:69], v[72:73]
	v_lshl_add_u64 v[66:67], v[66:67], 0, s[4:5]
	v_pk_mul_f32 v[50:51], v[50:51], v[54:55]
	v_lshl_add_u64 v[48:49], v[48:49], 0, s[4:5]
	v_pk_mul_f32 v[34:35], v[34:35], v[38:39]
	v_lshl_add_u64 v[32:33], v[32:33], 0, s[4:5]
	v_pk_mul_f32 v[18:19], v[18:19], v[22:23]
	v_lshl_add_u64 v[16:17], v[16:17], 0, s[4:5]
	s_waitcnt lgkmcnt(0)
	v_add_f32_e32 v0, v0, v1
	v_add_f32_e32 v2, v2, v3
	v_add_f32_e32 v4, v4, v5
	v_add_f32_e32 v6, v6, v7
	v_add_f32_e32 v8, v8, v9
	v_add_f32_e32 v10, v10, v11
	v_add_f32_e32 v12, v12, v13
	v_add_f32_e32 v14, v14, v15
	v_pk_mul_f32 v[132:133], v[132:133], v[134:135]
	v_lshl_add_u64 v[130:131], v[130:131], 0, s[78:79]
	v_pk_mul_f32 v[84:85], v[84:85], v[90:91]
	v_lshl_add_u64 v[82:83], v[82:83], 0, s[78:79]
	v_pk_mul_f32 v[68:69], v[68:69], v[70:71]
	v_lshl_add_u64 v[66:67], v[66:67], 0, s[78:79]
	v_pk_mul_f32 v[50:51], v[50:51], v[52:53]
	v_lshl_add_u64 v[48:49], v[48:49], 0, s[78:79]
	v_pk_mul_f32 v[34:35], v[34:35], v[36:37]
	v_lshl_add_u64 v[32:33], v[32:33], 0, s[78:79]
	v_pk_mul_f32 v[18:19], v[18:19], v[20:21]
	v_lshl_add_u64 v[16:17], v[16:17], 0, s[78:79]
	v_mov_b32_e32 v1, v0
	v_mov_b32_e32 v3, v2
	v_mov_b32_e32 v5, v4
	v_mov_b32_e32 v7, v6
	v_mov_b32_e32 v9, v8
	v_mov_b32_e32 v11, v10
	v_mov_b32_e32 v13, v12
	v_mov_b32_e32 v15, v14
	v_lshl_add_u64 v[150:151], v[150:151], 0, v[148:149]
	v_cvt_pk_bf16_f32 v141, v132, v133
	v_lshl_add_u64 v[130:131], v[130:131], 0, v[148:149]
	v_cvt_pk_bf16_f32 v117, v84, v85
	v_lshl_add_u64 v[82:83], v[82:83], 0, v[148:149]
	v_cvt_pk_bf16_f32 v77, v68, v69
	v_lshl_add_u64 v[66:67], v[66:67], 0, v[148:149]
	v_cvt_pk_bf16_f32 v59, v50, v51
	v_lshl_add_u64 v[48:49], v[48:49], 0, v[148:149]
	v_cvt_pk_bf16_f32 v43, v34, v35
	v_lshl_add_u64 v[32:33], v[32:33], 0, v[148:149]
	v_cvt_pk_bf16_f32 v27, v18, v19
	v_lshl_add_u64 v[16:17], v[16:17], 0, v[148:149]
	v_permlane32_swap_b32_e32 v0, v1
	v_permlane32_swap_b32_e32 v2, v3
	v_permlane32_swap_b32_e32 v4, v5
	v_permlane32_swap_b32_e32 v6, v7
	v_permlane32_swap_b32_e32 v8, v9
	v_permlane32_swap_b32_e32 v10, v11
	v_permlane32_swap_b32_e32 v12, v13
	v_permlane32_swap_b32_e32 v14, v15
	s_mov_b64 s[4:5], -1
	s_andn2_b64 vcc, exec, s[6:7]
	global_store_dwordx4 v[150:151], v[154:157], off
	global_store_dwordx4 v[130:131], v[138:141], off
	global_store_dwordx4 v[82:83], v[114:117], off
	global_store_dwordx4 v[66:67], v[74:77], off
	global_store_dwordx4 v[48:49], v[56:59], off
	global_store_dwordx4 v[32:33], v[40:43], off
	global_store_dwordx4 v[16:17], v[24:27], off
	s_cbranch_vccnz .LBB0_195
	s_andn2_b64 vcc, exec, s[10:11]
	s_cbranch_vccnz .LBB0_194
	s_barrier
	s_branch .LBB0_194

;     __device__ __forceinline__ void operator()(const f32x4 (&acc)[2][2][4][2], const Unit& u, int wr, int wc, int fr, int fq, const float (&)[8]) const {
;         const size_t off0 = (size_t)(u.pm * BM + wr * 64 + fr) * 1024 + u.pn * BM + wc * 32 + 8 * fq;
;         u32x4 raw[8][2];
;         if (!xf) {
; #pragma unroll
;             for (int r = 0; r < 8; ++r)
; #pragma unroll
;                 for (int bj = 0; bj < 2; ++bj) raw[r][bj] = *(const u32x4*)(hb + off0 + (size_t)(r >> 2) * (HALF * 1024) + (size_t)(r & 3) * (16 * 1024) + bj * HALF);
;         }
; #pragma unroll
;         for (int ai = 0; ai < 2; ++ai)
; #pragma unroll
;             for (int m = 0; m < 4; ++m) {
;                 const int row = u.pm * BM + ai * HALF + wr * 64 + m * 16 + fr; float sq = 0.f;
; #pragma unroll
;                 for (int bj = 0; bj < 2; ++bj) {
;                     const size_t off = off0 + (size_t)ai * (HALF * 1024) + (size_t)m * (16 * 1024) + bj * HALF;
;                     f32x4 b0, b1;
;                     if (xf) { b0 = *(const f32x4*)(xf + off); b1 = *(const f32x4*)(xf + off + 4); }
;                     else { const u32x4 w = raw[ai * 4 + m][bj];
;                         b0[0] = __uint_as_float(w.x << 16); b0[1] = __uint_as_float(w.x & 0xffff0000u); b0[2] = __uint_as_float(w.y << 16); b0[3] = __uint_as_float(w.y & 0xffff0000u);
;                         b1[0] = __uint_as_float(w.z << 16); b1[1] = __uint_as_float(w.z & 0xffff0000u); b1[2] = __uint_as_float(w.w << 16); b1[3] = __uint_as_float(w.w & 0xffff0000u); }
;                     const f32x4 o0 = b0 + acc[ai][bj][m][0] * alpha, o1 = b1 + acc[ai][bj][m][1] * alpha;
;                     if (outf) { *(f32x4*)(outf + off) = o0; *(f32x4*)(outf + off + 4) = o1; }
.LBB0_282:
	s_lshl_b32 s4, s48, 8
	v_mov_b32_e32 v0, v240
	v_mov_b32_e32 v244, v241
	s_add_i32 s4, s4, s42
	v_cndmask_b32_e64 v66, 0, 1, s[16:17]
	v_add_u32_e32 v106, s4, v0
	s_lshl_b32 s4, s2, 8
	s_ashr_i32 s5, s4, 31
	v_lshlrev_b32_e32 v2, 3, v244
	v_ashrrev_i32_e32 v107, 31, v106
	v_ashrrev_i32_e32 v3, 31, v2
	s_or_b64 s[4:5], s[4:5], s[18:19]
	v_lshlrev_b64 v[0:1], 10, v[106:107]
	v_lshl_add_u64 v[2:3], s[4:5], 0, v[2:3]
	v_lshl_add_u64 v[70:71], v[2:3], 0, v[0:1]
	v_lshl_add_u64 v[124:125], v[70:71], 1, s[86:87]
	v_add_co_u32_e32 v0, vcc, s80, v124
	global_load_dwordx4 v[60:63], v[124:125], off
	global_load_dwordx4 v[56:59], v[124:125], off offset:256
	v_addc_co_u32_e32 v1, vcc, 0, v125, vcc
	global_load_dwordx4 v[52:55], v[0:1], off
	global_load_dwordx4 v[48:51], v[0:1], off offset:256
	v_add_co_u32_e32 v0, vcc, s55, v124
	s_mov_b32 s4, 0x48000
	s_nop 0
	v_addc_co_u32_e32 v1, vcc, 0, v125, vcc
	global_load_dwordx4 v[44:47], v[0:1], off
	global_load_dwordx4 v[40:43], v[0:1], off offset:256
	v_add_co_u32_e32 v0, vcc, s60, v124
	v_cmp_ne_u32_e64 s[8:9], 1, v66
	s_nop 0
	v_addc_co_u32_e32 v1, vcc, 0, v125, vcc
	global_load_dwordx4 v[36:39], v[0:1], off
	global_load_dwordx4 v[32:35], v[0:1], off offset:256
	v_add_co_u32_e32 v0, vcc, s81, v124
	s_nop 1
	v_addc_co_u32_e32 v1, vcc, 0, v125, vcc
	global_load_dwordx4 v[28:31], v[0:1], off
	global_load_dwordx4 v[24:27], v[0:1], off offset:256
	v_add_co_u32_e32 v0, vcc, s4, v124
	s_mov_b32 s4, 0x50000
	s_nop 0
	v_addc_co_u32_e32 v1, vcc, 0, v125, vcc
	global_load_dwordx4 v[20:23], v[0:1], off
	global_load_dwordx4 v[16:19], v[0:1], off offset:256
	v_add_co_u32_e32 v0, vcc, s4, v124
	s_mov_b32 s4, 0x58000
	s_nop 0
	v_addc_co_u32_e32 v1, vcc, 0, v125, vcc
	global_load_dwordx4 v[12:15], v[0:1], off
	global_load_dwordx4 v[8:11], v[0:1], off offset:256
	v_add_co_u32_e32 v0, vcc, s4, v124
	s_nop 0
	s_nop 0
	v_addc_co_u32_e32 v1, vcc, 0, v125, vcc
	global_load_dwordx4 v[4:7], v[0:1], off
	s_nop 0
	global_load_dwordx4 v[0:3], v[0:1], off offset:256
	s_waitcnt vmcnt(8)
	v_lshlrev_b32_e32 v66, 16, v60
	v_and_b32_e32 v67, 0xffff0000, v60
	v_lshlrev_b32_e32 v60, 16, v61
	v_and_b32_e32 v61, 0xffff0000, v61
	v_lshlrev_b32_e32 v72, 16, v62
	v_and_b32_e32 v73, 0xffff0000, v62
	v_lshlrev_b32_e32 v62, 16, v63
	v_and_b32_e32 v63, 0xffff0000, v63
	s_andn2_b64 vcc, exec, s[16:17]
	v_pk_add_f32 v[68:69], v[128:129], v[60:61]
	v_pk_add_f32 v[66:67], v[218:219], v[66:67]
	v_pk_add_f32 v[62:63], v[222:223], v[62:63]
	v_pk_add_f32 v[60:61], v[226:227], v[72:73]
	v_lshl_add_u64 v[128:129], v[70:71], 2, s[14:15]
	s_cbranch_vccnz .LBB0_284
	global_store_dwordx4 v[128:129], v[66:69], off
	global_store_dwordx4 v[128:129], v[60:63], off offset:16

; __device__ __forceinline__ unsigned cvt_pk_bf16(float lo, float hi) { const f32x2c_ v = {lo, hi}; const bf16x2c_ b = __builtin_convertvector(v, bf16x2c_); return __builtin_bit_cast(unsigned, b); }
;     __device__ __forceinline__ void operator()(const f32x4 (&acc)[2][2][4][2], const Unit& u, int wr, int wc, int fr, int fq, const float (&)[8]) const {
;         const size_t off0 = (size_t)(u.pm * BM + wr * 64 + fr) * 1024 + u.pn * BM + wc * 32 + 8 * fq;
;         u32x4 raw[8][2];
;         if (!xf) {
; #pragma unroll
;             for (int r = 0; r < 8; ++r)
; #pragma unroll
;                 for (int bj = 0; bj < 2; ++bj) raw[r][bj] = *(const u32x4*)(hb + off0 + (size_t)(r >> 2) * (HALF * 1024) + (size_t)(r & 3) * (16 * 1024) + bj * HALF);
;         }
; #pragma unroll
;         for (int ai = 0; ai < 2; ++ai)
; #pragma unroll
;             for (int m = 0; m < 4; ++m) {
;                 const int row = u.pm * BM + ai * HALF + wr * 64 + m * 16 + fr; float sq = 0.f;
; #pragma unroll
;                 for (int bj = 0; bj < 2; ++bj) {
;                     const size_t off = off0 + (size_t)ai * (HALF * 1024) + (size_t)m * (16 * 1024) + bj * HALF;
;                     f32x4 b0, b1;
;                     if (xf) { b0 = *(const f32x4*)(xf + off); b1 = *(const f32x4*)(xf + off + 4); }
;                     else { const u32x4 w = raw[ai * 4 + m][bj];
;                         b0[0] = __uint_as_float(w.x << 16); b0[1] = __uint_as_float(w.x & 0xffff0000u); b0[2] = __uint_as_float(w.y << 16); b0[3] = __uint_as_float(w.y & 0xffff0000u);
;                         b1[0] = __uint_as_float(w.z << 16); b1[1] = __uint_as_float(w.z & 0xffff0000u); b1[2] = __uint_as_float(w.w << 16); b1[3] = __uint_as_float(w.w & 0xffff0000u); }
;                     const f32x4 o0 = b0 + acc[ai][bj][m][0] * alpha, o1 = b1 + acc[ai][bj][m][1] * alpha;
;                     if (outf) { *(f32x4*)(outf + off) = o0; *(f32x4*)(outf + off + 4) = o1; }
;                     sq += dot4(o0) + dot4(o1);
;                     u32x4 w; w.x = cvt_pk_bf16(o0[0], o0[1]); w.y = cvt_pk_bf16(o0[2], o0[3]); w.z = cvt_pk_bf16(o1[0], o1[1]); w.w = cvt_pk_bf16(o1[2], o1[3]);
;                     *(u32x4*)(hb + off) = w;
;                 }
;                 sq += sxor<16>(sq); sq = sum32(sq);
;                 if (fq == 0) ss[(size_t)row * 16 + u.pn * 4 + wc] = sq;
.LBB0_657:
	s_lshl_b32 s4, s44, 8
	v_mov_b32_e32 v130, v216
	v_mov_b32_e32 v224, v217
	s_add_i32 s4, s4, s37
	s_nop 0
	v_add_u32_e32 v212, s4, v130
	s_lshl_b32 s4, s2, 8
	s_ashr_i32 s5, s4, 31
	s_lshl_b64 s[4:5], s[4:5], 1
	v_lshlrev_b32_e32 v130, 3, v224
	s_add_u32 s4, s41, s4
	v_ashrrev_i32_e32 v213, 31, v212
	v_ashrrev_i32_e32 v131, 31, v130
	s_addc_u32 s5, s42, s5
	v_lshl_add_u64 v[130:131], v[130:131], 1, s[4:5]
	v_lshlrev_b64 v[132:133], 11, v[212:213]
	v_lshl_add_u64 v[214:215], v[130:131], 0, v[132:133]
	global_load_dwordx4 v[220:223], v[214:215], off
	global_load_dwordx4 v[186:189], v[214:215], off offset:256
	s_mov_b32 s4, 0x8000
	v_add_co_u32_e32 v130, vcc, s4, v214
	s_mov_b32 s4, 0x18000
	s_nop 0
	v_addc_co_u32_e32 v131, vcc, 0, v215, vcc
	global_load_dwordx4 v[182:185], v[130:131], off
	global_load_dwordx4 v[178:181], v[130:131], off offset:256
	v_add_co_u32_e32 v130, vcc, s55, v214
	s_nop 0
	s_nop 0
	v_addc_co_u32_e32 v131, vcc, 0, v215, vcc
	global_load_dwordx4 v[174:177], v[130:131], off
	global_load_dwordx4 v[170:173], v[130:131], off offset:256
	v_add_co_u32_e32 v130, vcc, s4, v214
	s_mov_b32 s4, 0x40000
	s_nop 0
	v_addc_co_u32_e32 v131, vcc, 0, v215, vcc
	global_load_dwordx4 v[166:169], v[130:131], off
	global_load_dwordx4 v[162:165], v[130:131], off offset:256
	v_add_co_u32_e32 v130, vcc, s4, v214
	s_mov_b32 s4, 0x48000
	s_nop 0
	v_addc_co_u32_e32 v131, vcc, 0, v215, vcc
	global_load_dwordx4 v[158:161], v[130:131], off
	global_load_dwordx4 v[154:157], v[130:131], off offset:256
	v_add_co_u32_e32 v130, vcc, s4, v214
	s_mov_b32 s4, 0x50000
	s_nop 0
	v_addc_co_u32_e32 v131, vcc, 0, v215, vcc
	global_load_dwordx4 v[150:153], v[130:131], off
	global_load_dwordx4 v[146:149], v[130:131], off offset:256
	v_add_co_u32_e32 v130, vcc, s4, v214
	s_mov_b32 s4, 0x58000
	s_nop 0
	v_addc_co_u32_e32 v131, vcc, 0, v215, vcc
	global_load_dwordx4 v[142:145], v[130:131], off
	global_load_dwordx4 v[138:141], v[130:131], off offset:256
	v_add_co_u32_e32 v130, vcc, s4, v214
	s_nop 0
	s_nop 0
	v_addc_co_u32_e32 v131, vcc, 0, v215, vcc
	global_load_dwordx4 v[134:137], v[130:131], off
	s_nop 0
	global_load_dwordx4 v[130:133], v[130:131], off offset:256
	s_waitcnt vmcnt(12)
	v_and_b32_e32 v225, 0xffff0000, v220
	v_lshlrev_b32_e32 v226, 16, v222
	v_cmp_eq_u32_e32 vcc, 0, v224
	v_lshlrev_b32_e32 v224, 16, v220
	v_lshlrev_b32_e32 v220, 16, v221
	v_and_b32_e32 v221, 0xffff0000, v221
	v_and_b32_e32 v227, 0xffff0000, v222
	v_lshlrev_b32_e32 v222, 16, v223
	v_and_b32_e32 v223, 0xffff0000, v223
	v_pk_add_f32 v[124:125], v[124:125], v[220:221]
	v_pk_add_f32 v[122:123], v[122:123], v[224:225]
	v_pk_add_f32 v[128:129], v[128:129], v[222:223]
	v_pk_add_f32 v[126:127], v[126:127], v[226:227]
	v_mul_f32_e32 v220, v123, v123
	v_mul_f32_e32 v221, v125, v125
	v_fmac_f32_e32 v220, v122, v122
	v_fmac_f32_e32 v221, v124, v124
	v_cvt_pk_bf16_f32 v122, v122, v123
	v_cvt_pk_bf16_f32 v123, v124, v125
	v_cvt_pk_bf16_f32 v124, v126, v127
	v_cvt_pk_bf16_f32 v125, v128, v129
	v_add_f32_e32 v220, v220, v221
	v_mul_f32_e32 v221, v127, v127
	v_mul_f32_e32 v222, v129, v129
	global_store_dwordx4 v[214:215], v[122:125], off
	v_fmac_f32_e32 v221, v126, v126
	v_fmac_f32_e32 v222, v128, v128
	v_lshlrev_b32_e32 v122, 16, v186
	v_and_b32_e32 v123, 0xffff0000, v186
	v_lshlrev_b32_e32 v124, 16, v187
	v_and_b32_e32 v125, 0xffff0000, v187
	v_lshlrev_b32_e32 v126, 16, v188
	v_and_b32_e32 v127, 0xffff0000, v188
	v_lshlrev_b32_e32 v128, 16, v189
	v_and_b32_e32 v129, 0xffff0000, v189
	v_pk_add_f32 v[120:121], v[120:121], v[124:125]
	v_pk_add_f32 v[118:119], v[118:119], v[122:123]
	v_pk_add_f32 v[122:123], v[116:117], v[128:129]
	v_pk_add_f32 v[116:117], v[114:115], v[126:127]
	v_mul_f32_e32 v114, v119, v119
	v_mul_f32_e32 v115, v121, v121
	v_fmac_f32_e32 v114, v118, v118
	v_fmac_f32_e32 v115, v120, v120
	v_add_f32_e32 v114, v114, v115
	v_mul_f32_e32 v115, v117, v117
	v_mul_f32_e32 v124, v123, v123
	v_fmac_f32_e32 v115, v116, v116
	v_fmac_f32_e32 v124, v122, v122
	v_add_f32_e32 v221, v221, v222
	v_add_f32_e32 v115, v115, v124
	v_add_f32_e32 v220, v220, v221
	v_add_f32_e32 v114, v114, v115
	v_add_f32_e32 v124, v220, v114
	v_cvt_pk_bf16_f32 v114, v118, v119
	v_cvt_pk_bf16_f32 v115, v120, v121
	v_cvt_pk_bf16_f32 v116, v116, v117
	v_cvt_pk_bf16_f32 v117, v122, v123
	global_store_dwordx4 v[214:215], v[114:117], off offset:256
	ds_swizzle_b32 v114, v124 offset:swizzle(SWAP,16)
	s_lshl_b32 s4, s2, 2
	s_ashr_i32 s5, s4, 31
	s_waitcnt lgkmcnt(0)
	v_add_f32_e32 v114, v124, v114
	v_mov_b32_e32 v115, v114
	s_nop 1
	v_permlane32_swap_b32_e32 v114, v115
	s_and_saveexec_b64 s[22:23], vcc
	s_cbranch_execz .LBB0_659
	v_lshlrev_b64 v[116:117], 6, v[212:213]
	v_lshl_add_u64 v[116:117], s[74:75], 0, v[116:117]
	v_lshl_add_u64 v[116:117], s[4:5], 2, v[116:117]
	s_lshl_b32 s78, s35, 2
	v_lshl_add_u64 v[116:117], v[116:117], 0, s[78:79]
	v_add_f32_e32 v114, v114, v115
	global_store_dword v[116:117], v114, off

; __device__ __forceinline__ unsigned cvt_pk_bf16(float lo, float hi) { const f32x2c_ v = {lo, hi}; const bf16x2c_ b = __builtin_convertvector(v, bf16x2c_); return __builtin_bit_cast(unsigned, b); }
; template <int N> __device__ __forceinline__ float sxor(float v) { static_assert(N > 0 && N < 32, "sxor"); return __int_as_float(__builtin_amdgcn_ds_swizzle(__float_as_int(v), 0x1f | (N << 10))); }
; __device__ __forceinline__ float sum32(float v) { const auto rr = __builtin_amdgcn_permlane32_swap(__float_as_uint(v), __float_as_uint(v), false, false); return __uint_as_float(rr[0]) + __uint_as_float(rr[1]); }
;     __device__ __forceinline__ void pre_issue(const Unit& u, int wr, int fr, int fq, f32x4 (&raw)[8]) const { stat_issue(ss, u, wr, fr, fq, raw); }
;     __device__ __forceinline__ void pre_issue(const Unit& u, int wr, int fr, int fq, f32x4 (&raw)[8]) const {
;         const bool isq = u.pn < 3; const float* ssp = isq ? ssq : sskv; const float invn = isq ? 1.0f / 256.0f : 1.0f / 128.0f;
; #pragma unroll
;         for (int r = 0; r < 8; ++r) raw[r][0] = ssp[(size_t)(u.pm * BM + (r >> 2) * HALF + wr * 64 + (r & 3) * 16 + fr) * 4 + fq];
;         raw[0][1] = invn;
;     }
;     __device__ __forceinline__ void pre_finish(const f32x4 (&raw)[8], float (&rs)[8]) const {
; #pragma unroll
;         for (int r = 0; r < 8; ++r) { float sp = raw[r][0]; sp += sxor<16>(sp); sp = sum32(sp); rs[r] = __builtin_amdgcn_rsqf(sp * raw[0][1] + EPS); }
;     }
;     __device__ __forceinline__ void operator()(const f32x4 (&acc)[2][2][4][2], const Unit& u, int wr, int wc, int fr, int fq, const float (&rsv)[8]) const {
; #pragma unroll
;         for (int ai = 0; ai < 2; ++ai)
; #pragma unroll
;             for (int m = 0; m < 4; ++m) {
;                 const int row = u.pm * BM + ai * HALF + wr * 64 + m * 16 + fr;
;                 const float rs = rsv[ai * 4 + m];
; #pragma unroll
;                 for (int bj = 0; bj < 2; ++bj) {
;                     const f32x4 v0 = acc[ai][bj][m][0] * rs, v1 = acc[ai][bj][m][1] * rs;
;                     u32x4 w; w.x = cvt_pk_bf16(v0[0], v0[1]); w.y = cvt_pk_bf16(v0[2], v0[3]); w.z = cvt_pk_bf16(v1[0], v1[1]); w.w = cvt_pk_bf16(v1[2], v1[3]);
;                     *(u32x4*)(O + (size_t)row * ldc + u.pn * BM + bj * HALF + wc * 32 + 8 * fq) = w;
.LBB0_908:
	s_and_b64 s[8:9], s[8:9], exec
	s_cselect_b32 s8, s40, s42
	s_cselect_b32 s13, s12, s41
	s_cmp_lt_i32 s8, 3
	s_cselect_b64 s[8:9], -1, 0
	v_mov_b32_e32 v149, v141
	v_mov_b32_e32 v156, v143
	s_and_b64 s[18:19], s[8:9], exec
	s_cselect_b32 s18, s29, s31
	s_cselect_b32 s19, s28, s30
	v_add_u32_e32 v155, s25, v149
	v_mov_b32_e32 v158, s19
	v_mov_b32_e32 v159, s18
	v_ashrrev_i32_e32 v157, 31, v156
	v_lshl_add_u32 v160, s13, 8, v155
	v_lshl_add_u64 v[158:159], v[156:157], 2, v[158:159]
	v_ashrrev_i32_e32 v161, 31, v160
	v_lshl_add_u64 v[162:163], v[160:161], 4, v[158:159]
	global_load_dword v164, v[162:163], off
	v_add_u32_e32 v162, 16, v160
	v_ashrrev_i32_e32 v163, 31, v162
	v_lshl_add_u64 v[162:163], v[162:163], 4, v[158:159]
	global_load_dword v165, v[162:163], off
	v_add_u32_e32 v162, 32, v160
	v_ashrrev_i32_e32 v163, 31, v162
	v_lshl_add_u64 v[162:163], v[162:163], 4, v[158:159]
	global_load_dword v166, v[162:163], off
	v_add_u32_e32 v162, 48, v160
	v_ashrrev_i32_e32 v163, 31, v162
	v_lshl_add_u64 v[162:163], v[162:163], 4, v[158:159]
	global_load_dword v167, v[162:163], off
	v_add_u32_e32 v162, 0x80, v160
	v_ashrrev_i32_e32 v163, 31, v162
	v_lshl_add_u64 v[162:163], v[162:163], 4, v[158:159]
	global_load_dword v168, v[162:163], off
	v_add_u32_e32 v162, 0x90, v160
	v_ashrrev_i32_e32 v163, 31, v162
	v_lshl_add_u64 v[162:163], v[162:163], 4, v[158:159]
	global_load_dword v153, v[162:163], off
	v_add_u32_e32 v162, 0xa0, v160
	v_ashrrev_i32_e32 v163, 31, v162
	v_lshl_add_u64 v[162:163], v[162:163], 4, v[158:159]
	global_load_dword v151, v[162:163], off
	v_add_u32_e32 v160, 0xb0, v160
	v_ashrrev_i32_e32 v161, 31, v160
	v_lshl_add_u64 v[158:159], v[160:161], 4, v[158:159]
	global_load_dword v149, v[158:159], off
	v_lshl_add_u32 v155, s41, 8, v155
	s_lshl_b32 s18, s42, 8
	v_pk_mul_f32 v[128:129], v[154:155], v[128:129] op_sel_hi:[0,1]
	v_pk_mul_f32 v[126:127], v[154:155], v[126:127] op_sel_hi:[0,1]
	v_pk_mul_f32 v[122:123], v[154:155], v[122:123] op_sel_hi:[0,1]
	s_ashr_i32 s19, s18, 31
	v_pk_mul_f32 v[124:125], v[154:155], v[124:125] op_sel_hi:[0,1]
	v_cvt_pk_bf16_f32 v126, v126, v127
	v_cvt_pk_bf16_f32 v127, v128, v129
	v_cvt_pk_bf16_f32 v128, v122, v123
	v_mov_b64_e32 v[122:123], s[80:81]
	v_lshlrev_b32_e32 v156, 3, v156
	v_cvt_pk_bf16_f32 v129, v124, v125
	v_mad_i64_i32 v[124:125], s[20:21], v155, s85, v[122:123]
	s_lshl_b64 s[18:19], s[18:19], 1
	v_ashrrev_i32_e32 v157, 31, v156
	v_lshl_add_u64 v[124:125], v[124:125], 0, s[18:19]
	v_lshl_add_u64 v[158:159], v[124:125], 0, s[78:79]
	v_lshlrev_b64 v[124:125], 1, v[156:157]
	v_lshl_add_u64 v[156:157], v[158:159], 0, v[124:125]
	global_store_dwordx4 v[156:157], v[126:129], off
	v_pk_mul_f32 v[116:117], v[154:155], v[116:117] op_sel_hi:[0,1]
	v_pk_mul_f32 v[114:115], v[154:155], v[114:115] op_sel_hi:[0,1]
	v_pk_mul_f32 v[126:127], v[154:155], v[108:109] op_sel_hi:[0,1]
	v_pk_mul_f32 v[108:109], v[154:155], v[106:107] op_sel_hi:[0,1]
	v_cvt_pk_bf16_f32 v106, v114, v115
	v_cvt_pk_bf16_f32 v107, v116, v117
	v_cvt_pk_bf16_f32 v108, v108, v109
	v_cvt_pk_bf16_f32 v109, v126, v127
	global_store_dwordx4 v[156:157], v[106:109], off offset:256
	v_add_u32_e32 v114, 16, v155
	v_pk_mul_f32 v[60:61], v[146:147], v[60:61] op_sel_hi:[0,1]
	v_pk_mul_f32 v[62:63], v[146:147], v[62:63] op_sel_hi:[0,1]
	v_pk_mul_f32 v[50:51], v[146:147], v[50:51] op_sel_hi:[0,1]
	v_pk_mul_f32 v[48:49], v[146:147], v[48:49] op_sel_hi:[0,1]
	v_pk_mul_f32 v[44:45], v[144:145], v[44:45] op_sel_hi:[0,1]
	v_pk_mul_f32 v[46:47], v[144:145], v[46:47] op_sel_hi:[0,1]
	v_pk_mul_f32 v[34:35], v[144:145], v[34:35] op_sel_hi:[0,1]
	v_pk_mul_f32 v[32:33], v[144:145], v[32:33] op_sel_hi:[0,1]
	v_pk_mul_f32 v[28:29], v[142:143], v[28:29] op_sel_hi:[0,1]
	v_pk_mul_f32 v[30:31], v[142:143], v[30:31] op_sel_hi:[0,1]
	v_pk_mul_f32 v[18:19], v[142:143], v[18:19] op_sel_hi:[0,1]
	v_pk_mul_f32 v[16:17], v[142:143], v[16:17] op_sel_hi:[0,1]
	v_pk_mul_f32 v[12:13], v[140:141], v[12:13] op_sel_hi:[0,1]
	v_pk_mul_f32 v[14:15], v[140:141], v[14:15] op_sel_hi:[0,1]
	v_pk_mul_f32 v[6:7], v[140:141], v[6:7] op_sel_hi:[0,1]
	v_pk_mul_f32 v[4:5], v[140:141], v[4:5] op_sel_hi:[0,1]
	s_and_b64 vcc, exec, s[6:7]
	s_waitcnt vmcnt(2)
	v_pk_mul_f32 v[108:109], v[152:153], v[120:121] op_sel_hi:[0,1]
	v_pk_mul_f32 v[106:107], v[152:153], v[118:119] op_sel_hi:[0,1]
	v_pk_mul_f32 v[110:111], v[152:153], v[110:111] op_sel_hi:[0,1]
	v_cvt_pk_bf16_f32 v106, v106, v107
	v_cvt_pk_bf16_f32 v107, v108, v109
	v_cvt_pk_bf16_f32 v108, v110, v111
	v_mad_i64_i32 v[110:111], s[20:21], v114, s85, v[122:123]
	v_lshl_add_u64 v[110:111], v[110:111], 0, s[18:19]
	v_pk_mul_f32 v[112:113], v[152:153], v[112:113] op_sel_hi:[0,1]
	v_lshl_add_u64 v[110:111], v[110:111], 0, s[78:79]
	v_cvt_pk_bf16_f32 v109, v112, v113
	v_lshl_add_u64 v[110:111], v[110:111], 0, v[124:125]
	global_store_dwordx4 v[110:111], v[106:109], off
	v_pk_mul_f32 v[100:101], v[152:153], v[100:101] op_sel_hi:[0,1]
	v_pk_mul_f32 v[98:99], v[152:153], v[98:99] op_sel_hi:[0,1]
	v_pk_mul_f32 v[106:107], v[152:153], v[92:93] op_sel_hi:[0,1]
	v_pk_mul_f32 v[92:93], v[152:153], v[90:91] op_sel_hi:[0,1]
	v_cvt_pk_bf16_f32 v90, v98, v99
	v_cvt_pk_bf16_f32 v91, v100, v101
	v_cvt_pk_bf16_f32 v92, v92, v93
	v_cvt_pk_bf16_f32 v93, v106, v107
	global_store_dwordx4 v[110:111], v[90:93], off offset:256
	v_add_u32_e32 v98, 32, v155
	v_pk_mul_f32 v[94:95], v[150:151], v[94:95] op_sel_hi:[0,1]
	v_pk_mul_f32 v[92:93], v[150:151], v[104:105] op_sel_hi:[0,1]
	v_pk_mul_f32 v[90:91], v[150:151], v[102:103] op_sel_hi:[0,1]
	v_cvt_pk_bf16_f32 v90, v90, v91
	v_cvt_pk_bf16_f32 v91, v92, v93
	v_cvt_pk_bf16_f32 v92, v94, v95
; __device__ __forceinline__ unsigned cvt_pk_bf16(float lo, float hi) { const f32x2c_ v = {lo, hi}; const bf16x2c_ b = __builtin_convertvector(v, bf16x2c_); return __builtin_bit_cast(unsigned, b); }
; template <int N> __device__ __forceinline__ float sxor(float v) { static_assert(N > 0 && N < 32, "sxor"); return __int_as_float(__builtin_amdgcn_ds_swizzle(__float_as_int(v), 0x1f | (N << 10))); }
; __device__ __forceinline__ float sum32(float v) { const auto rr = __builtin_amdgcn_permlane32_swap(__float_as_uint(v), __float_as_uint(v), false, false); return __uint_as_float(rr[0]) + __uint_as_float(rr[1]); }
;     __device__ __forceinline__ void pre_finish(const f32x4 (&raw)[8], float (&rs)[8]) const {
;     ...
;         for (int r = 0; r < 8; ++r) { float sp = raw[r][0]; sp += sxor<16>(sp); sp = sum32(sp); rs[r] = __builtin_amdgcn_rsqf(sp * raw[0][1] + EPS); }
;     }
;     __device__ __forceinline__ void operator()(const f32x4 (&acc)[2][2][4][2], const Unit& u, int wr, int wc, int fr, int fq, const float (&rsv)[8]) const {
; #pragma unroll
;         for (int ai = 0; ai < 2; ++ai)
; #pragma unroll
;             for (int m = 0; m < 4; ++m) {
;                 const int row = u.pm * BM + ai * HALF + wr * 64 + m * 16 + fr;
;                 const float rs = rsv[ai * 4 + m];
; #pragma unroll
;                 for (int bj = 0; bj < 2; ++bj) {
;                     const f32x4 v0 = acc[ai][bj][m][0] * rs, v1 = acc[ai][bj][m][1] * rs;
;                     u32x4 w; w.x = cvt_pk_bf16(v0[0], v0[1]); w.y = cvt_pk_bf16(v0[2], v0[3]); w.z = cvt_pk_bf16(v1[0], v1[1]); w.w = cvt_pk_bf16(v1[2], v1[3]);
;                     *(u32x4*)(O + (size_t)row * ldc + u.pn * BM + bj * HALF + wc * 32 + 8 * fq) = w;
	v_mad_i64_i32 v[94:95], s[20:21], v98, s85, v[122:123]
	v_lshl_add_u64 v[94:95], v[94:95], 0, s[18:19]
	v_pk_mul_f32 v[96:97], v[150:151], v[96:97] op_sel_hi:[0,1]
	v_lshl_add_u64 v[94:95], v[94:95], 0, s[78:79]
	v_cvt_pk_bf16_f32 v93, v96, v97
	v_lshl_add_u64 v[94:95], v[94:95], 0, v[124:125]
	global_store_dwordx4 v[94:95], v[90:93], off
	v_pk_mul_f32 v[84:85], v[150:151], v[84:85] op_sel_hi:[0,1]
	v_pk_mul_f32 v[82:83], v[150:151], v[82:83] op_sel_hi:[0,1]
	v_pk_mul_f32 v[90:91], v[150:151], v[76:77] op_sel_hi:[0,1]
	v_pk_mul_f32 v[76:77], v[150:151], v[74:75] op_sel_hi:[0,1]
	v_cvt_pk_bf16_f32 v74, v82, v83
	v_cvt_pk_bf16_f32 v75, v84, v85
	v_cvt_pk_bf16_f32 v76, v76, v77
	v_cvt_pk_bf16_f32 v77, v90, v91
	global_store_dwordx4 v[94:95], v[74:77], off offset:256
	v_add_u32_e32 v82, 48, v155
	v_pk_mul_f32 v[78:79], v[148:149], v[78:79] op_sel_hi:[0,1]
	v_pk_mul_f32 v[76:77], v[148:149], v[88:89] op_sel_hi:[0,1]
	v_pk_mul_f32 v[74:75], v[148:149], v[86:87] op_sel_hi:[0,1]
	v_cvt_pk_bf16_f32 v74, v74, v75
	v_cvt_pk_bf16_f32 v75, v76, v77
	v_cvt_pk_bf16_f32 v76, v78, v79
	v_mad_i64_i32 v[78:79], s[20:21], v82, s85, v[122:123]
	v_lshl_add_u64 v[78:79], v[78:79], 0, s[18:19]
	v_pk_mul_f32 v[80:81], v[148:149], v[80:81] op_sel_hi:[0,1]
	v_lshl_add_u64 v[78:79], v[78:79], 0, s[78:79]
	v_cvt_pk_bf16_f32 v77, v80, v81
	v_lshl_add_u64 v[78:79], v[78:79], 0, v[124:125]
	global_store_dwordx4 v[78:79], v[74:77], off
	v_pk_mul_f32 v[72:73], v[148:149], v[72:73] op_sel_hi:[0,1]
	v_pk_mul_f32 v[70:71], v[148:149], v[70:71] op_sel_hi:[0,1]
	v_pk_mul_f32 v[74:75], v[148:149], v[68:69] op_sel_hi:[0,1]
	v_pk_mul_f32 v[68:69], v[148:149], v[66:67] op_sel_hi:[0,1]
	v_cvt_pk_bf16_f32 v66, v70, v71
	v_cvt_pk_bf16_f32 v67, v72, v73
	v_cvt_pk_bf16_f32 v68, v68, v69
	v_cvt_pk_bf16_f32 v69, v74, v75
	global_store_dwordx4 v[78:79], v[66:69], off offset:256
	s_nop 1
	v_add_u32_e32 v68, 0x80, v155
	v_pk_mul_f32 v[66:67], v[146:147], v[58:59] op_sel_hi:[0,1]
	v_pk_mul_f32 v[58:59], v[146:147], v[56:57] op_sel_hi:[0,1]
	v_cvt_pk_bf16_f32 v56, v60, v61
	v_mad_i64_i32 v[60:61], s[20:21], v68, s85, v[122:123]
	v_lshl_add_u64 v[60:61], v[60:61], 0, s[18:19]
	v_lshl_add_u64 v[60:61], v[60:61], 0, s[78:79]
	v_cvt_pk_bf16_f32 v57, v62, v63
	v_cvt_pk_bf16_f32 v58, v58, v59
	v_cvt_pk_bf16_f32 v59, v66, v67
	v_lshl_add_u64 v[60:61], v[60:61], 0, v[124:125]
	global_store_dwordx4 v[60:61], v[56:59], off
	s_nop 1
	v_pk_mul_f32 v[56:57], v[146:147], v[42:43] op_sel_hi:[0,1]
	v_pk_mul_f32 v[42:43], v[146:147], v[40:41] op_sel_hi:[0,1]
	v_cvt_pk_bf16_f32 v40, v48, v49
	v_cvt_pk_bf16_f32 v41, v50, v51
	v_cvt_pk_bf16_f32 v42, v42, v43
	v_cvt_pk_bf16_f32 v43, v56, v57
	global_store_dwordx4 v[60:61], v[40:43], off offset:256
	v_add_u32_e32 v48, 0x90, v155
	s_nop 0
	v_pk_mul_f32 v[42:43], v[144:145], v[54:55] op_sel_hi:[0,1]
	v_pk_mul_f32 v[40:41], v[144:145], v[52:53] op_sel_hi:[0,1]
	v_cvt_pk_bf16_f32 v40, v40, v41
	v_cvt_pk_bf16_f32 v41, v42, v43
	v_cvt_pk_bf16_f32 v42, v44, v45
	v_mad_i64_i32 v[44:45], s[20:21], v48, s85, v[122:123]
	v_lshl_add_u64 v[44:45], v[44:45], 0, s[18:19]
	v_lshl_add_u64 v[44:45], v[44:45], 0, s[78:79]
	v_cvt_pk_bf16_f32 v43, v46, v47
	v_lshl_add_u64 v[44:45], v[44:45], 0, v[124:125]
	global_store_dwordx4 v[44:45], v[40:43], off
	s_nop 1
	v_pk_mul_f32 v[40:41], v[144:145], v[26:27] op_sel_hi:[0,1]
	v_pk_mul_f32 v[26:27], v[144:145], v[24:25] op_sel_hi:[0,1]
	v_cvt_pk_bf16_f32 v24, v32, v33
	v_cvt_pk_bf16_f32 v25, v34, v35
	v_cvt_pk_bf16_f32 v26, v26, v27
	v_cvt_pk_bf16_f32 v27, v40, v41
	global_store_dwordx4 v[44:45], v[24:27], off offset:256
	v_add_u32_e32 v32, 0xa0, v155
	s_nop 0
	v_pk_mul_f32 v[26:27], v[142:143], v[38:39] op_sel_hi:[0,1]
	v_pk_mul_f32 v[24:25], v[142:143], v[36:37] op_sel_hi:[0,1]
	v_cvt_pk_bf16_f32 v24, v24, v25
	v_cvt_pk_bf16_f32 v25, v26, v27
	v_cvt_pk_bf16_f32 v26, v28, v29
	v_mad_i64_i32 v[28:29], s[20:21], v32, s85, v[122:123]
	v_lshl_add_u64 v[28:29], v[28:29], 0, s[18:19]
	v_lshl_add_u64 v[28:29], v[28:29], 0, s[78:79]
	v_cvt_pk_bf16_f32 v27, v30, v31
	v_lshl_add_u64 v[28:29], v[28:29], 0, v[124:125]
	global_store_dwordx4 v[28:29], v[24:27], off
	s_nop 1
	v_pk_mul_f32 v[24:25], v[142:143], v[10:11] op_sel_hi:[0,1]
	v_pk_mul_f32 v[10:11], v[142:143], v[8:9] op_sel_hi:[0,1]
	v_cvt_pk_bf16_f32 v8, v16, v17
	v_cvt_pk_bf16_f32 v9, v18, v19
	v_cvt_pk_bf16_f32 v10, v10, v11
	v_cvt_pk_bf16_f32 v11, v24, v25
	global_store_dwordx4 v[28:29], v[8:11], off offset:256
	v_add_u32_e32 v16, 0xb0, v155
	s_nop 0
	v_pk_mul_f32 v[10:11], v[140:141], v[22:23] op_sel_hi:[0,1]
	v_pk_mul_f32 v[8:9], v[140:141], v[20:21] op_sel_hi:[0,1]
	v_cvt_pk_bf16_f32 v8, v8, v9
	v_cvt_pk_bf16_f32 v9, v10, v11
	v_cvt_pk_bf16_f32 v10, v12, v13
	v_mad_i64_i32 v[12:13], s[20:21], v16, s85, v[122:123]
	v_lshl_add_u64 v[12:13], v[12:13], 0, s[18:19]
	v_lshl_add_u64 v[12:13], v[12:13], 0, s[78:79]
	v_cvt_pk_bf16_f32 v11, v14, v15
	v_lshl_add_u64 v[12:13], v[12:13], 0, v[124:125]
	global_store_dwordx4 v[12:13], v[8:11], off
	ds_swizzle_b32 v10, v153 offset:swizzle(SWAP,16)
	ds_swizzle_b32 v14, v149 offset:swizzle(SWAP,16)
	v_pk_mul_f32 v[8:9], v[140:141], v[2:3] op_sel_hi:[0,1]
	v_pk_mul_f32 v[2:3], v[140:141], v[0:1] op_sel_hi:[0,1]
	v_cvt_pk_bf16_f32 v0, v4, v5
	v_cvt_pk_bf16_f32 v1, v6, v7
	v_cvt_pk_bf16_f32 v2, v2, v3
	v_cvt_pk_bf16_f32 v3, v8, v9
	global_store_dwordx4 v[12:13], v[0:3], off offset:256
	ds_swizzle_b32 v0, v164 offset:swizzle(SWAP,16)
	ds_swizzle_b32 v2, v165 offset:swizzle(SWAP,16)
	ds_swizzle_b32 v4, v166 offset:swizzle(SWAP,16)
	ds_swizzle_b32 v6, v167 offset:swizzle(SWAP,16)
	ds_swizzle_b32 v8, v168 offset:swizzle(SWAP,16)
	ds_swizzle_b32 v12, v151 offset:swizzle(SWAP,16)
	s_waitcnt lgkmcnt(5)
	v_add_f32_e32 v0, v164, v0
	s_waitcnt lgkmcnt(4)
	v_add_f32_e32 v2, v165, v2
	s_waitcnt lgkmcnt(3)
	v_add_f32_e32 v4, v166, v4
	s_waitcnt lgkmcnt(2)
	v_add_f32_e32 v6, v167, v6
	s_waitcnt lgkmcnt(1)
	v_add_f32_e32 v8, v168, v8
	v_add_f32_e32 v10, v153, v10
	s_waitcnt lgkmcnt(0)
	v_add_f32_e32 v12, v151, v12
	v_add_f32_e32 v14, v149, v14
	v_mov_b32_e32 v1, v0
	v_mov_b32_e32 v3, v2
	v_mov_b32_e32 v5, v4
	v_mov_b32_e32 v7, v6
	v_mov_b32_e32 v9, v8
	v_mov_b32_e32 v11, v10
	v_mov_b32_e32 v13, v12
	v_mov_b32_e32 v15, v14
	v_permlane32_swap_b32_e32 v0, v1
	v_permlane32_swap_b32_e32 v2, v3
	v_permlane32_swap_b32_e32 v4, v5
	v_permlane32_swap_b32_e32 v6, v7
	v_permlane32_swap_b32_e32 v8, v9
	v_permlane32_swap_b32_e32 v10, v11
	v_permlane32_swap_b32_e32 v12, v13
	v_permlane32_swap_b32_e32 v14, v15
	s_mov_b64 s[18:19], -1
	s_cbranch_vccnz .LBB0_899
	s_cmp_gt_i32 s40, 2
	s_cselect_b32 s43, 2, 4
	s_andn2_b64 vcc, exec, s[4:5]
	s_cbranch_vccnz .LBB0_898
	s_barrier
	s_branch .LBB0_898

; __device__ __forceinline__ float max32(float v) { const auto rr = __builtin_amdgcn_permlane32_swap(__float_as_uint(v), __float_as_uint(v), false, false); return fmaxf(__uint_as_float(rr[0]), __uint_as_float(rr[1])); }
; __device__ __forceinline__ void attn_unit(int bh, int qb, const bf16_t* QKV, const bf16_t* KF, const float* cstab, const float* qg, bf16_t* MIX, LAS unsigned char* lds) {
;     ...
;             float mx = fmaxf(fmaxf(p[0], p[1]), fmaxf(p[2], p[3]));
; #pragma unroll
;             for (int r = 4; r < 16; r += 4) mx = fmaxf(mx, fmaxf(fmaxf(p[r], p[r + 1]), fmaxf(p[r + 2], p[r + 3])));
;             mx = pg8::max32(mx);
;             if (key0 == 0 || __any(mx > 4.0f)) {
;                 const float dl = (key0 == 0) ? mx : fmaxf(mx, 0.f), f = __builtin_amdgcn_exp2f(-dl);
;                 mrun += dl; lrun *= f;
; #pragma unroll
;                 for (int r = 0; r < 16; ++r) { o0[r] *= f; o1[r] *= f; p[r] -= dl; negm[r] = -mrun; }
;             }
.LBB0_1051:
	s_nop 8
	v_max3_f32 v120, v48, v49, v50
	v_max3_f32 v121, v51, v52, v53
	v_max3_f32 v122, v54, v55, v56
	v_max3_f32 v123, v57, v58, v59
	v_max3_f32 v120, v120, v121, v122
	v_max3_f32 v121, v60, v61, v62
	v_max3_f32 v120, v120, v123, v121
	v_max_f32_e32 v120, v120, v63
	v_cmp_lt_f32_e32 vcc, 4.0, v120
	s_cbranch_vccz .LBB0_1053
	v_mov_b32_e32 v121, v120
	s_nop 1
	v_permlane32_swap_b32_e32 v120, v121
	v_max_f32_e32 v120, v120, v121
	v_max_f32_e32 v32, v120, v120
	v_max_f32_e32 v34, 0, v32
	v_exp_f32_e64 v120, -v34
	v_add_f32_e32 v106, v106, v34
	v_xor_b32_e32 v32, 0x80000000, v106
	v_pk_add_f32 v[48:49], v[48:49], v[34:35] op_sel_hi:[1,0] neg_lo:[0,1] neg_hi:[0,1]
	v_pk_add_f32 v[50:51], v[50:51], v[34:35] op_sel_hi:[1,0] neg_lo:[0,1] neg_hi:[0,1]
	v_pk_add_f32 v[52:53], v[52:53], v[34:35] op_sel_hi:[1,0] neg_lo:[0,1] neg_hi:[0,1]
	v_pk_add_f32 v[54:55], v[54:55], v[34:35] op_sel_hi:[1,0] neg_lo:[0,1] neg_hi:[0,1]
	v_pk_add_f32 v[56:57], v[56:57], v[34:35] op_sel_hi:[1,0] neg_lo:[0,1] neg_hi:[0,1]
	v_pk_add_f32 v[58:59], v[58:59], v[34:35] op_sel_hi:[1,0] neg_lo:[0,1] neg_hi:[0,1]
	v_pk_add_f32 v[60:61], v[60:61], v[34:35] op_sel_hi:[1,0] neg_lo:[0,1] neg_hi:[0,1]
	v_pk_mul_f32 v[14:15], v[14:15], v[120:121] op_sel_hi:[1,0]
	v_pk_mul_f32 v[12:13], v[12:13], v[120:121] op_sel_hi:[1,0]
	v_pk_mul_f32 v[10:11], v[10:11], v[120:121] op_sel_hi:[1,0]
	v_pk_mul_f32 v[8:9], v[8:9], v[120:121] op_sel_hi:[1,0]
	v_pk_mul_f32 v[6:7], v[6:7], v[120:121] op_sel_hi:[1,0]
	v_pk_mul_f32 v[4:5], v[4:5], v[120:121] op_sel_hi:[1,0]
	v_pk_mul_f32 v[2:3], v[2:3], v[120:121] op_sel_hi:[1,0]
	v_pk_mul_f32 v[0:1], v[0:1], v[120:121] op_sel_hi:[1,0]
	v_pk_mul_f32 v[30:31], v[30:31], v[120:121] op_sel_hi:[1,0]
	v_pk_mul_f32 v[28:29], v[28:29], v[120:121] op_sel_hi:[1,0]
	v_pk_mul_f32 v[26:27], v[26:27], v[120:121] op_sel_hi:[1,0]
	v_pk_mul_f32 v[24:25], v[24:25], v[120:121] op_sel_hi:[1,0]
	v_pk_mul_f32 v[22:23], v[22:23], v[120:121] op_sel_hi:[1,0]
	v_pk_mul_f32 v[20:21], v[20:21], v[120:121] op_sel_hi:[1,0]
	v_pk_mul_f32 v[18:19], v[18:19], v[120:121] op_sel_hi:[1,0]
	v_pk_mul_f32 v[16:17], v[16:17], v[120:121] op_sel_hi:[1,0]
	v_pk_add_f32 v[62:63], v[62:63], v[34:35] op_sel_hi:[1,0] neg_lo:[0,1] neg_hi:[0,1]
	v_mov_b32_e32 v33, v32
	v_mov_b32_e32 v34, v32
	v_mov_b32_e32 v35, v32
	v_mov_b32_e32 v36, v32
	v_mov_b32_e32 v37, v32
	v_mov_b32_e32 v38, v32
	v_mov_b32_e32 v39, v32
	v_mov_b32_e32 v40, v32
	v_mov_b32_e32 v41, v32
	v_mov_b32_e32 v42, v32
	v_mov_b32_e32 v43, v32
	v_mov_b32_e32 v44, v32
	v_mov_b32_e32 v45, v32
	v_mov_b32_e32 v46, v32
	v_mov_b32_e32 v47, v32
	v_mul_f32_e32 v107, v107, v120

; __device__ __forceinline__ float max32(float v) { const auto rr = __builtin_amdgcn_permlane32_swap(__float_as_uint(v), __float_as_uint(v), false, false); return fmaxf(__uint_as_float(rr[0]), __uint_as_float(rr[1])); }
; __device__ __forceinline__ void attn_unit(int bh, int qb, const bf16_t* QKV, const bf16_t* KF, const float* cstab, const float* qg, bf16_t* MIX, LAS unsigned char* lds) {
;     ...
;             float mx = fmaxf(fmaxf(p[0], p[1]), fmaxf(p[2], p[3]));
; #pragma unroll
;             for (int r = 4; r < 16; r += 4) mx = fmaxf(mx, fmaxf(fmaxf(p[r], p[r + 1]), fmaxf(p[r + 2], p[r + 3])));
;             mx = pg8::max32(mx);
;             if (key0 == 0 || __any(mx > 4.0f)) {
;                 const float dl = (key0 == 0) ? mx : fmaxf(mx, 0.f), f = __builtin_amdgcn_exp2f(-dl);
;                 mrun += dl; lrun *= f;
; #pragma unroll
;                 for (int r = 0; r < 16; ++r) { o0[r] *= f; o1[r] *= f; p[r] -= dl; negm[r] = -mrun; }
;             }
.LBB0_1064:
	s_nop 7
	v_max3_f32 v121, v48, v49, v50
	v_max3_f32 v122, v51, v52, v53
	v_max3_f32 v123, v54, v55, v56
	v_max3_f32 v124, v57, v58, v59
	v_max3_f32 v121, v121, v122, v123
	v_max3_f32 v122, v60, v61, v62
	v_max3_f32 v121, v121, v124, v122
	v_max_f32_e32 v121, v121, v63
	v_cmp_lt_f32_e32 vcc, 4.0, v121
	s_cbranch_vccz .LBB0_1066
	v_mov_b32_e32 v122, v121
	s_nop 1
	v_permlane32_swap_b32_e32 v121, v122
	v_max_f32_e32 v121, v121, v122
	v_max_f32_e32 v32, v121, v121
	v_max_f32_e32 v34, 0, v32
	v_exp_f32_e64 v122, -v34
	v_add_f32_e32 v106, v106, v34
	v_xor_b32_e32 v32, 0x80000000, v106
	v_pk_add_f32 v[48:49], v[48:49], v[34:35] op_sel_hi:[1,0] neg_lo:[0,1] neg_hi:[0,1]
	v_pk_add_f32 v[50:51], v[50:51], v[34:35] op_sel_hi:[1,0] neg_lo:[0,1] neg_hi:[0,1]
	v_pk_add_f32 v[52:53], v[52:53], v[34:35] op_sel_hi:[1,0] neg_lo:[0,1] neg_hi:[0,1]
	v_pk_add_f32 v[54:55], v[54:55], v[34:35] op_sel_hi:[1,0] neg_lo:[0,1] neg_hi:[0,1]
	v_pk_add_f32 v[56:57], v[56:57], v[34:35] op_sel_hi:[1,0] neg_lo:[0,1] neg_hi:[0,1]
	v_pk_add_f32 v[58:59], v[58:59], v[34:35] op_sel_hi:[1,0] neg_lo:[0,1] neg_hi:[0,1]
	v_pk_add_f32 v[60:61], v[60:61], v[34:35] op_sel_hi:[1,0] neg_lo:[0,1] neg_hi:[0,1]
	v_pk_mul_f32 v[14:15], v[14:15], v[122:123] op_sel_hi:[1,0]
	v_pk_mul_f32 v[12:13], v[12:13], v[122:123] op_sel_hi:[1,0]
	v_pk_mul_f32 v[10:11], v[10:11], v[122:123] op_sel_hi:[1,0]
	v_pk_mul_f32 v[8:9], v[8:9], v[122:123] op_sel_hi:[1,0]
	v_pk_mul_f32 v[6:7], v[6:7], v[122:123] op_sel_hi:[1,0]
	v_pk_mul_f32 v[4:5], v[4:5], v[122:123] op_sel_hi:[1,0]
	v_pk_mul_f32 v[2:3], v[2:3], v[122:123] op_sel_hi:[1,0]
	v_pk_mul_f32 v[0:1], v[0:1], v[122:123] op_sel_hi:[1,0]
	v_pk_mul_f32 v[30:31], v[30:31], v[122:123] op_sel_hi:[1,0]
	v_pk_mul_f32 v[28:29], v[28:29], v[122:123] op_sel_hi:[1,0]
	v_pk_mul_f32 v[26:27], v[26:27], v[122:123] op_sel_hi:[1,0]
	v_pk_mul_f32 v[24:25], v[24:25], v[122:123] op_sel_hi:[1,0]
	v_pk_mul_f32 v[22:23], v[22:23], v[122:123] op_sel_hi:[1,0]
	v_pk_mul_f32 v[20:21], v[20:21], v[122:123] op_sel_hi:[1,0]
	v_pk_mul_f32 v[18:19], v[18:19], v[122:123] op_sel_hi:[1,0]
	v_pk_mul_f32 v[16:17], v[16:17], v[122:123] op_sel_hi:[1,0]
	v_pk_add_f32 v[62:63], v[62:63], v[34:35] op_sel_hi:[1,0] neg_lo:[0,1] neg_hi:[0,1]
	v_mov_b32_e32 v33, v32
	v_mov_b32_e32 v34, v32
	v_mov_b32_e32 v35, v32
	v_mov_b32_e32 v36, v32
	v_mov_b32_e32 v37, v32
	v_mov_b32_e32 v38, v32
	v_mov_b32_e32 v39, v32
	v_mov_b32_e32 v40, v32
	v_mov_b32_e32 v41, v32
	v_mov_b32_e32 v42, v32
	v_mov_b32_e32 v43, v32
	v_mov_b32_e32 v44, v32
	v_mov_b32_e32 v45, v32
	v_mov_b32_e32 v46, v32
	v_mov_b32_e32 v47, v32
	v_mul_f32_e32 v107, v107, v122

; __device__ __forceinline__ float max32(float v) { const auto rr = __builtin_amdgcn_permlane32_swap(__float_as_uint(v), __float_as_uint(v), false, false); return fmaxf(__uint_as_float(rr[0]), __uint_as_float(rr[1])); }
; __device__ __forceinline__ void attn_unit(int bh, int qb, const bf16_t* QKV, const bf16_t* KF, const float* cstab, const float* qg, bf16_t* MIX, LAS unsigned char* lds) {
;     ...
;             float mx = fmaxf(fmaxf(p[0], p[1]), fmaxf(p[2], p[3]));
; #pragma unroll
;             for (int r = 4; r < 16; r += 4) mx = fmaxf(mx, fmaxf(fmaxf(p[r], p[r + 1]), fmaxf(p[r + 2], p[r + 3])));
;             mx = pg8::max32(mx);
;             if (key0 == 0 || __any(mx > 4.0f)) {
;                 const float dl = (key0 == 0) ? mx : fmaxf(mx, 0.f), f = __builtin_amdgcn_exp2f(-dl);
;                 mrun += dl; lrun *= f;
; #pragma unroll
;                 for (int r = 0; r < 16; ++r) { o0[r] *= f; o1[r] *= f; p[r] -= dl; negm[r] = -mrun; }
;             }
.LBB0_1071:
	s_nop 7
	v_max3_f32 v120, v48, v49, v50
	v_max3_f32 v121, v51, v52, v53
	v_max3_f32 v122, v54, v55, v56
	v_max3_f32 v123, v57, v58, v59
	v_max3_f32 v120, v120, v121, v122
	v_max3_f32 v121, v60, v61, v62
	v_max3_f32 v120, v120, v123, v121
	v_max_f32_e32 v120, v120, v63
	v_cmp_lt_f32_e32 vcc, 4.0, v120
	s_cbranch_vccz .LBB0_1073
	v_mov_b32_e32 v121, v120
	s_nop 1
	v_permlane32_swap_b32_e32 v120, v121
	v_max_f32_e32 v120, v120, v121
	v_max_f32_e32 v32, v120, v120
	v_max_f32_e32 v34, 0, v32
	v_exp_f32_e64 v120, -v34
	v_add_f32_e32 v106, v106, v34
	v_xor_b32_e32 v32, 0x80000000, v106
	v_pk_add_f32 v[48:49], v[48:49], v[34:35] op_sel_hi:[1,0] neg_lo:[0,1] neg_hi:[0,1]
	v_pk_add_f32 v[50:51], v[50:51], v[34:35] op_sel_hi:[1,0] neg_lo:[0,1] neg_hi:[0,1]
	v_pk_add_f32 v[52:53], v[52:53], v[34:35] op_sel_hi:[1,0] neg_lo:[0,1] neg_hi:[0,1]
	v_pk_add_f32 v[54:55], v[54:55], v[34:35] op_sel_hi:[1,0] neg_lo:[0,1] neg_hi:[0,1]
	v_pk_add_f32 v[56:57], v[56:57], v[34:35] op_sel_hi:[1,0] neg_lo:[0,1] neg_hi:[0,1]
	v_pk_add_f32 v[58:59], v[58:59], v[34:35] op_sel_hi:[1,0] neg_lo:[0,1] neg_hi:[0,1]
	v_pk_add_f32 v[60:61], v[60:61], v[34:35] op_sel_hi:[1,0] neg_lo:[0,1] neg_hi:[0,1]
	v_pk_mul_f32 v[14:15], v[14:15], v[120:121] op_sel_hi:[1,0]
	v_pk_mul_f32 v[12:13], v[12:13], v[120:121] op_sel_hi:[1,0]
	v_pk_mul_f32 v[10:11], v[10:11], v[120:121] op_sel_hi:[1,0]
	v_pk_mul_f32 v[8:9], v[8:9], v[120:121] op_sel_hi:[1,0]
	v_pk_mul_f32 v[6:7], v[6:7], v[120:121] op_sel_hi:[1,0]
	v_pk_mul_f32 v[4:5], v[4:5], v[120:121] op_sel_hi:[1,0]
	v_pk_mul_f32 v[2:3], v[2:3], v[120:121] op_sel_hi:[1,0]
	v_pk_mul_f32 v[0:1], v[0:1], v[120:121] op_sel_hi:[1,0]
	v_pk_mul_f32 v[30:31], v[30:31], v[120:121] op_sel_hi:[1,0]
	v_pk_mul_f32 v[28:29], v[28:29], v[120:121] op_sel_hi:[1,0]
	v_pk_mul_f32 v[26:27], v[26:27], v[120:121] op_sel_hi:[1,0]
	v_pk_mul_f32 v[24:25], v[24:25], v[120:121] op_sel_hi:[1,0]
	v_pk_mul_f32 v[22:23], v[22:23], v[120:121] op_sel_hi:[1,0]
	v_pk_mul_f32 v[20:21], v[20:21], v[120:121] op_sel_hi:[1,0]
	v_pk_mul_f32 v[18:19], v[18:19], v[120:121] op_sel_hi:[1,0]
	v_pk_mul_f32 v[16:17], v[16:17], v[120:121] op_sel_hi:[1,0]
	v_pk_add_f32 v[62:63], v[62:63], v[34:35] op_sel_hi:[1,0] neg_lo:[0,1] neg_hi:[0,1]
	v_mov_b32_e32 v33, v32
	v_mov_b32_e32 v34, v32
	v_mov_b32_e32 v35, v32
	v_mov_b32_e32 v36, v32
	v_mov_b32_e32 v37, v32
	v_mov_b32_e32 v38, v32
	v_mov_b32_e32 v39, v32
	v_mov_b32_e32 v40, v32
	v_mov_b32_e32 v41, v32
	v_mov_b32_e32 v42, v32
	v_mov_b32_e32 v43, v32
	v_mov_b32_e32 v44, v32
	v_mov_b32_e32 v45, v32
	v_mov_b32_e32 v46, v32
	v_mov_b32_e32 v47, v32
	v_mul_f32_e32 v107, v107, v120

; __device__ __forceinline__ unsigned cvt_pk_bf16(float lo, float hi) { const f32x2c_ v = {lo, hi}; const bf16x2c_ b = __builtin_convertvector(v, bf16x2c_); return __builtin_bit_cast(unsigned, b); }
;     __device__ __forceinline__ void operator()(const f32x4 (&acc)[2][2][4][2], const Unit& u, int wr, int wc, int fr, int fq, const float (&)[8]) const {
;         const size_t off0 = (size_t)(u.pm * BM + wr * 64 + fr) * 1024 + u.pn * BM + wc * 32 + 8 * fq;
;         u32x4 raw[8][2];
;         if (!xf) {
; #pragma unroll
;             for (int r = 0; r < 8; ++r)
; #pragma unroll
;                 for (int bj = 0; bj < 2; ++bj) raw[r][bj] = *(const u32x4*)(hb + off0 + (size_t)(r >> 2) * (HALF * 1024) + (size_t)(r & 3) * (16 * 1024) + bj * HALF);
;         }
; #pragma unroll
;         for (int ai = 0; ai < 2; ++ai)
; #pragma unroll
;             for (int m = 0; m < 4; ++m) {
;                 const int row = u.pm * BM + ai * HALF + wr * 64 + m * 16 + fr; float sq = 0.f;
; #pragma unroll
;                 for (int bj = 0; bj < 2; ++bj) {
;                     const size_t off = off0 + (size_t)ai * (HALF * 1024) + (size_t)m * (16 * 1024) + bj * HALF;
;                     f32x4 b0, b1;
;                     if (xf) { b0 = *(const f32x4*)(xf + off); b1 = *(const f32x4*)(xf + off + 4); }
;                     else { const u32x4 w = raw[ai * 4 + m][bj];
;                         b0[0] = __uint_as_float(w.x << 16); b0[1] = __uint_as_float(w.x & 0xffff0000u); b0[2] = __uint_as_float(w.y << 16); b0[3] = __uint_as_float(w.y & 0xffff0000u);
;                         b1[0] = __uint_as_float(w.z << 16); b1[1] = __uint_as_float(w.z & 0xffff0000u); b1[2] = __uint_as_float(w.w << 16); b1[3] = __uint_as_float(w.w & 0xffff0000u); }
;                     const f32x4 o0 = b0 + acc[ai][bj][m][0] * alpha, o1 = b1 + acc[ai][bj][m][1] * alpha;
;                     if (outf) { *(f32x4*)(outf + off) = o0; *(f32x4*)(outf + off + 4) = o1; }
;                     sq += dot4(o0) + dot4(o1);
;                     u32x4 w; w.x = cvt_pk_bf16(o0[0], o0[1]); w.y = cvt_pk_bf16(o0[2], o0[3]); w.z = cvt_pk_bf16(o1[0], o1[1]); w.w = cvt_pk_bf16(o1[2], o1[3]);
;                     *(u32x4*)(hb + off) = w;
;                 }
;                 sq += sxor<16>(sq); sq = sum32(sq);
;                 if (fq == 0) ss[(size_t)row * 16 + u.pn * 4 + wc] = sq;
.LBB0_1190:
	s_lshl_b32 s4, s44, 8
	v_mov_b32_e32 v130, v216
	v_mov_b32_e32 v224, v217
	s_add_i32 s4, s4, s37
	s_nop 0
	v_add_u32_e32 v212, s4, v130
	s_lshl_b32 s4, s2, 8
	s_ashr_i32 s5, s4, 31
	s_lshl_b64 s[4:5], s[4:5], 1
	v_lshlrev_b32_e32 v130, 3, v224
	s_add_u32 s4, s41, s4
	v_ashrrev_i32_e32 v213, 31, v212
	v_ashrrev_i32_e32 v131, 31, v130
	s_addc_u32 s5, s42, s5
	v_lshl_add_u64 v[130:131], v[130:131], 1, s[4:5]
	v_lshlrev_b64 v[132:133], 11, v[212:213]
	v_lshl_add_u64 v[214:215], v[130:131], 0, v[132:133]
	global_load_dwordx4 v[220:223], v[214:215], off
	global_load_dwordx4 v[186:189], v[214:215], off offset:256
	v_add_co_u32_e32 v130, vcc, s80, v214
	s_mov_b32 s4, 0x48000
	s_nop 0
	v_addc_co_u32_e32 v131, vcc, 0, v215, vcc
	global_load_dwordx4 v[182:185], v[130:131], off
	global_load_dwordx4 v[178:181], v[130:131], off offset:256
	v_add_co_u32_e32 v130, vcc, s53, v214
	s_nop 0
	s_nop 0
	v_addc_co_u32_e32 v131, vcc, 0, v215, vcc
	global_load_dwordx4 v[174:177], v[130:131], off
	global_load_dwordx4 v[170:173], v[130:131], off offset:256
	v_add_co_u32_e32 v130, vcc, s60, v214
	s_nop 0
	s_nop 0
	v_addc_co_u32_e32 v131, vcc, 0, v215, vcc
	global_load_dwordx4 v[166:169], v[130:131], off
	global_load_dwordx4 v[162:165], v[130:131], off offset:256
	v_add_co_u32_e32 v130, vcc, s81, v214
	s_nop 0
	s_nop 0
	v_addc_co_u32_e32 v131, vcc, 0, v215, vcc
	global_load_dwordx4 v[158:161], v[130:131], off
	global_load_dwordx4 v[154:157], v[130:131], off offset:256
	v_add_co_u32_e32 v130, vcc, s4, v214
	s_mov_b32 s4, 0x50000
	s_nop 0
	v_addc_co_u32_e32 v131, vcc, 0, v215, vcc
	global_load_dwordx4 v[150:153], v[130:131], off
	global_load_dwordx4 v[146:149], v[130:131], off offset:256
	v_add_co_u32_e32 v130, vcc, s4, v214
	s_mov_b32 s4, 0x58000
	s_nop 0
	v_addc_co_u32_e32 v131, vcc, 0, v215, vcc
	global_load_dwordx4 v[142:145], v[130:131], off
	global_load_dwordx4 v[138:141], v[130:131], off offset:256
	v_add_co_u32_e32 v130, vcc, s4, v214
	s_nop 0
	s_nop 0
	v_addc_co_u32_e32 v131, vcc, 0, v215, vcc
	global_load_dwordx4 v[134:137], v[130:131], off
	s_nop 0
	global_load_dwordx4 v[130:133], v[130:131], off offset:256
	s_waitcnt vmcnt(12)
	v_and_b32_e32 v225, 0xffff0000, v220
	v_lshlrev_b32_e32 v226, 16, v222
	v_and_b32_e32 v227, 0xffff0000, v222
	v_lshlrev_b32_e32 v222, 16, v223
	v_cmp_eq_u32_e32 vcc, 0, v224
	v_lshlrev_b32_e32 v224, 16, v220
	v_lshlrev_b32_e32 v220, 16, v221
	v_and_b32_e32 v221, 0xffff0000, v221
	v_and_b32_e32 v223, 0xffff0000, v223
	v_pk_add_f32 v[124:125], v[124:125], v[220:221]
	v_pk_add_f32 v[122:123], v[122:123], v[224:225]
	v_pk_add_f32 v[128:129], v[128:129], v[222:223]
	v_pk_add_f32 v[126:127], v[126:127], v[226:227]
	v_mul_f32_e32 v220, v123, v123
	v_mul_f32_e32 v221, v125, v125
	v_fmac_f32_e32 v220, v122, v122
	v_fmac_f32_e32 v221, v124, v124
	v_cvt_pk_bf16_f32 v122, v122, v123
	v_cvt_pk_bf16_f32 v123, v124, v125
	v_cvt_pk_bf16_f32 v124, v126, v127
	v_cvt_pk_bf16_f32 v125, v128, v129
	v_add_f32_e32 v220, v220, v221
	v_mul_f32_e32 v221, v127, v127
	v_mul_f32_e32 v222, v129, v129
	global_store_dwordx4 v[214:215], v[122:125], off
	v_fmac_f32_e32 v221, v126, v126
	v_fmac_f32_e32 v222, v128, v128
	v_lshlrev_b32_e32 v122, 16, v186
	v_and_b32_e32 v123, 0xffff0000, v186
	v_lshlrev_b32_e32 v124, 16, v187
	v_and_b32_e32 v125, 0xffff0000, v187
	v_lshlrev_b32_e32 v126, 16, v188
	v_and_b32_e32 v127, 0xffff0000, v188
	v_lshlrev_b32_e32 v128, 16, v189
	v_and_b32_e32 v129, 0xffff0000, v189
	v_pk_add_f32 v[120:121], v[120:121], v[124:125]
	v_pk_add_f32 v[118:119], v[118:119], v[122:123]
	v_pk_add_f32 v[122:123], v[116:117], v[128:129]
	v_pk_add_f32 v[116:117], v[114:115], v[126:127]
	v_mul_f32_e32 v114, v119, v119
	v_mul_f32_e32 v115, v121, v121
	v_fmac_f32_e32 v114, v118, v118
	v_fmac_f32_e32 v115, v120, v120
	v_add_f32_e32 v114, v114, v115
	v_mul_f32_e32 v115, v117, v117
	v_mul_f32_e32 v124, v123, v123
	v_fmac_f32_e32 v115, v116, v116
	v_fmac_f32_e32 v124, v122, v122
	v_add_f32_e32 v221, v221, v222
	v_add_f32_e32 v115, v115, v124
	v_add_f32_e32 v220, v220, v221
	v_add_f32_e32 v114, v114, v115
	v_add_f32_e32 v124, v220, v114
	v_cvt_pk_bf16_f32 v114, v118, v119
	v_cvt_pk_bf16_f32 v115, v120, v121
	v_cvt_pk_bf16_f32 v116, v116, v117
	v_cvt_pk_bf16_f32 v117, v122, v123
	global_store_dwordx4 v[214:215], v[114:117], off offset:256
	ds_swizzle_b32 v114, v124 offset:swizzle(SWAP,16)
	s_lshl_b32 s4, s2, 2
	s_ashr_i32 s5, s4, 31
	s_waitcnt lgkmcnt(0)
	v_add_f32_e32 v114, v124, v114
	v_mov_b32_e32 v115, v114
	s_nop 1
	v_permlane32_swap_b32_e32 v114, v115
	s_and_saveexec_b64 s[22:23], vcc
	s_cbranch_execz .LBB0_1192
	v_lshlrev_b64 v[116:117], 6, v[212:213]
	v_lshl_add_u64 v[116:117], s[74:75], 0, v[116:117]
	v_lshl_add_u64 v[116:117], s[4:5], 2, v[116:117]
	s_lshl_b32 s78, s35, 2
	v_lshl_add_u64 v[116:117], v[116:117], 0, s[78:79]
	v_add_f32_e32 v114, v114, v115
	global_store_dword v[116:117], v114, off
